# MFMA issue order inside each 16-MFMA group changed to a serpentine so every consecutive pair shares one operand fragment (operand-toggle / power experiment)
# baseline (speedup 1.0000x reference)
; #define PG8_STAGE(bufoff, gbase, voff) do { const char* _gb = (const char*)(gbase); asm volatile("" : "+s"(_gb));     \
;         _Pragma("unroll") for (int _i = 0; _i < 2; ++_i) \
;         __builtin_amdgcn_global_load_lds((const unsigned*)(_gb + (voff)[_i]), (LAS unsigned*)(lds + (bufoff) + ldsw + _i * 8192), 16, 0, 0); } while (0)
; #define PG8_LDA(dst, b, h) do { _Pragma("unroll") for (int m = 0; m < 4; ++m) _Pragma("unroll") for (int k = 0; k < 2; ++k) dst[m][k] = *(const LAS bf16x8*)(lds + PG8_SA(b, h) + aoff + m * 2048 + k * 1024); } while (0)
; #define PG8_LDB(dst, b, h) do { _Pragma("unroll") for (int n = 0; n < 2; ++n) _Pragma("unroll") for (int k = 0; k < 2; ++k) dst[n][k] = *(const LAS bf16x8*)(lds + PG8_SB(b, h) + boff + n * 2048 + k * 1024); } while (0)
; #define PG8_WAIT_V(n) asm volatile("s_waitcnt vmcnt(" #n ")" ::: "memory")
; #define PG8_WAIT_L(n) asm volatile("s_waitcnt lgkmcnt(" #n ")" ::: "memory")
; #define PG8_BAR __builtin_amdgcn_s_barrier()
; #define PG8_SCHED __builtin_amdgcn_sched_barrier(0)
; template <class Epi>
; __device__ __forceinline__ void gemm_phase(LAS unsigned char* lds, const Gemm g, const StaticOrder& S, const Epi& E) {
;     ...
;             PG8_LDB(B0, 0, 0); PG8_LDB(B1, 0, 1); PG8_SCHED; PG8_LDA(At, 0, 0); PG8_STAGE(PG8_SA(1, 1), a1 + hstepA, voffA);
;             PG8_WAIT_V(8); PG8_WAIT_L(0); PG8_BAR; PG8_MMA2(0, At, B0, B1); PG8_BAR; PG8_SCHED;
;             PG8_LDA(At, 0, 1); PG8_STAGE(PG8_SB(0, 0), b2, voffB); PG8_STAGE(PG8_SB(0, 1), b2 + hstepB, voffB); PG8_STAGE(PG8_SA(0, 0), a2, voffA);
;             PG8_WAIT_V(8); PG8_WAIT_L(0); PG8_BAR; PG8_MMA2(1, At, B0, B1); PG8_BAR; PG8_SCHED;
.LBB0_109:
	ds_read_b128 v[150:153], v135
	ds_read_b128 v[154:157], v135 offset:1024
	ds_read_b128 v[158:161], v135 offset:2048
	ds_read_b128 v[162:165], v135 offset:3072
	ds_read_b128 v[166:169], v143
	ds_read_b128 v[170:173], v143 offset:1024
	ds_read_b128 v[174:177], v143 offset:2048
	ds_read_b128 v[178:181], v143 offset:3072
	s_cmp_eq_u32 s67, 28
	s_cselect_b32 s50, s62, s65
	s_cselect_b32 s51, s41, s66
	s_cselect_b32 s48, s42, s63
	s_cselect_b32 s49, s43, s64
	s_add_u32 s6, s50, 0x80
	s_addc_u32 s7, s51, 0
	s_add_u32 s52, s65, s20
	s_addc_u32 s53, s66, s21
	s_add_u32 s52, s52, 0xffffff80
	s_addc_u32 s53, s53, -1
	s_add_i32 m0, s25, 0xc000
	ds_read_b128 v[182:185], v145
	ds_read_b128 v[186:189], v145 offset:1024
	ds_read_b128 v[190:193], v145 offset:2048
	ds_read_b128 v[194:197], v145 offset:3072
	ds_read_b128 v[198:201], v145 offset:4096
	ds_read_b128 v[202:205], v145 offset:5120
	ds_read_b128 v[206:209], v145 offset:6144
	ds_read_b128 v[210:213], v145 offset:7168
	s_nop 0
	global_load_lds_dwordx4 v134, s[52:53]
	s_add_i32 m0, s25, 0xe000
	s_nop 0
	global_load_lds_dwordx4 v130, s[52:53]
	s_waitcnt vmcnt(8)
	s_waitcnt lgkmcnt(0)
	s_barrier
	s_setprio 1
	s_waitcnt lgkmcnt(0)
	v_mfma_f32_16x16x32_bf16 v[124:127], v[150:153], v[182:185], v[124:127]
	v_mfma_f32_16x16x32_bf16 v[120:123], v[158:161], v[182:185], v[120:123]
	v_mfma_f32_16x16x32_bf16 v[104:107], v[158:161], v[190:193], v[104:107]
	v_mfma_f32_16x16x32_bf16 v[108:111], v[150:153], v[190:193], v[108:111]
	v_mfma_f32_16x16x32_bf16 v[92:95], v[150:153], v[198:201], v[92:95]
	v_mfma_f32_16x16x32_bf16 v[88:91], v[158:161], v[198:201], v[88:91]
	v_mfma_f32_16x16x32_bf16 v[72:75], v[158:161], v[206:209], v[72:75]
	v_mfma_f32_16x16x32_bf16 v[76:79], v[150:153], v[206:209], v[76:79]
	v_mfma_f32_16x16x32_bf16 v[68:71], v[166:169], v[206:209], v[68:71]
	v_mfma_f32_16x16x32_bf16 v[64:67], v[174:177], v[206:209], v[64:67]
	v_mfma_f32_16x16x32_bf16 v[80:83], v[174:177], v[198:201], v[80:83]
	v_mfma_f32_16x16x32_bf16 v[84:87], v[166:169], v[198:201], v[84:87]
	v_mfma_f32_16x16x32_bf16 v[100:103], v[166:169], v[190:193], v[100:103]
	v_mfma_f32_16x16x32_bf16 v[96:99], v[174:177], v[190:193], v[96:99]
	v_mfma_f32_16x16x32_bf16 v[112:115], v[174:177], v[182:185], v[112:115]
	v_mfma_f32_16x16x32_bf16 v[116:119], v[166:169], v[182:185], v[116:119]
	v_mfma_f32_16x16x32_bf16 v[124:127], v[154:157], v[186:189], v[124:127]
	v_mfma_f32_16x16x32_bf16 v[120:123], v[162:165], v[186:189], v[120:123]
	v_mfma_f32_16x16x32_bf16 v[104:107], v[162:165], v[194:197], v[104:107]
	v_mfma_f32_16x16x32_bf16 v[108:111], v[154:157], v[194:197], v[108:111]
	v_mfma_f32_16x16x32_bf16 v[92:95], v[154:157], v[202:205], v[92:95]
	v_mfma_f32_16x16x32_bf16 v[88:91], v[162:165], v[202:205], v[88:91]
	v_mfma_f32_16x16x32_bf16 v[72:75], v[162:165], v[210:213], v[72:75]
	v_mfma_f32_16x16x32_bf16 v[76:79], v[154:157], v[210:213], v[76:79]
	v_mfma_f32_16x16x32_bf16 v[68:71], v[170:173], v[210:213], v[68:71]
	v_mfma_f32_16x16x32_bf16 v[64:67], v[178:181], v[210:213], v[64:67]
	v_mfma_f32_16x16x32_bf16 v[80:83], v[178:181], v[202:205], v[80:83]
	v_mfma_f32_16x16x32_bf16 v[84:87], v[170:173], v[202:205], v[84:87]
	v_mfma_f32_16x16x32_bf16 v[100:103], v[170:173], v[194:197], v[100:103]
	v_mfma_f32_16x16x32_bf16 v[96:99], v[178:181], v[194:197], v[96:99]
	v_mfma_f32_16x16x32_bf16 v[112:115], v[178:181], v[186:189], v[112:115]
	v_mfma_f32_16x16x32_bf16 v[116:119], v[170:173], v[186:189], v[116:119]
	s_setprio 0
	s_barrier
	s_add_i32 s68, s57, s3
	s_mov_b64 s[52:53], s[48:49]
	s_mov_b32 m0, s68
	ds_read_b128 v[182:185], v145 offset:16384
	ds_read_b128 v[186:189], v145 offset:17408
	ds_read_b128 v[190:193], v145 offset:18432
	ds_read_b128 v[194:197], v145 offset:19456
	ds_read_b128 v[198:201], v145 offset:20480
	ds_read_b128 v[202:205], v145 offset:21504
	ds_read_b128 v[206:209], v145 offset:22528
	ds_read_b128 v[210:213], v145 offset:23552
	s_nop 0
	global_load_lds_dwordx4 v149, s[52:53]
	s_add_i32 m0, s68, 0x2000
	s_nop 0
	global_load_lds_dwordx4 v128, s[52:53]
	s_add_u32 s52, s48, s14
	s_addc_u32 s53, s49, s15
	s_add_i32 s70, s58, s3
	s_mov_b64 s[68:69], s[52:53]
	s_mov_b32 m0, s70
	s_nop 0
	global_load_lds_dwordx4 v149, s[68:69]
	s_add_i32 m0, s70, 0x2000
	s_nop 0
	global_load_lds_dwordx4 v128, s[68:69]
	s_mov_b64 s[68:69], s[50:51]
	s_mov_b32 m0, s25
	s_nop 0
	global_load_lds_dwordx4 v134, s[68:69]
	s_mov_b32 m0, s26
	s_nop 0
	global_load_lds_dwordx4 v130, s[68:69]
	s_waitcnt vmcnt(8)
	s_waitcnt lgkmcnt(0)
	s_barrier
	s_setprio 1
	s_waitcnt lgkmcnt(0)
	v_mfma_f32_16x16x32_bf16 v[60:63], v[150:153], v[182:185], v[60:63]
	v_mfma_f32_16x16x32_bf16 v[56:59], v[158:161], v[182:185], v[56:59]
	v_mfma_f32_16x16x32_bf16 v[40:43], v[158:161], v[190:193], v[40:43]
	v_mfma_f32_16x16x32_bf16 v[44:47], v[150:153], v[190:193], v[44:47]
	v_mfma_f32_16x16x32_bf16 v[28:31], v[150:153], v[198:201], v[28:31]
	v_mfma_f32_16x16x32_bf16 v[24:27], v[158:161], v[198:201], v[24:27]
	v_mfma_f32_16x16x32_bf16 v[8:11], v[158:161], v[206:209], v[8:11]
	v_mfma_f32_16x16x32_bf16 v[12:15], v[150:153], v[206:209], v[12:15]
	v_mfma_f32_16x16x32_bf16 v[4:7], v[166:169], v[206:209], v[4:7]
	v_mfma_f32_16x16x32_bf16 v[0:3], v[174:177], v[206:209], v[0:3]
	v_mfma_f32_16x16x32_bf16 v[16:19], v[174:177], v[198:201], v[16:19]
	v_mfma_f32_16x16x32_bf16 v[20:23], v[166:169], v[198:201], v[20:23]
	v_mfma_f32_16x16x32_bf16 v[36:39], v[166:169], v[190:193], v[36:39]
	v_mfma_f32_16x16x32_bf16 v[32:35], v[174:177], v[190:193], v[32:35]
	v_mfma_f32_16x16x32_bf16 v[48:51], v[174:177], v[182:185], v[48:51]
	v_mfma_f32_16x16x32_bf16 v[52:55], v[166:169], v[182:185], v[52:55]
	v_mfma_f32_16x16x32_bf16 v[60:63], v[154:157], v[186:189], v[60:63]
	v_mfma_f32_16x16x32_bf16 v[56:59], v[162:165], v[186:189], v[56:59]
	v_mfma_f32_16x16x32_bf16 v[40:43], v[162:165], v[194:197], v[40:43]
	v_mfma_f32_16x16x32_bf16 v[44:47], v[154:157], v[194:197], v[44:47]
	v_mfma_f32_16x16x32_bf16 v[28:31], v[154:157], v[202:205], v[28:31]
	v_mfma_f32_16x16x32_bf16 v[24:27], v[162:165], v[202:205], v[24:27]
	v_mfma_f32_16x16x32_bf16 v[8:11], v[162:165], v[210:213], v[8:11]
	v_mfma_f32_16x16x32_bf16 v[12:15], v[154:157], v[210:213], v[12:15]
	v_mfma_f32_16x16x32_bf16 v[4:7], v[170:173], v[210:213], v[4:7]
	v_mfma_f32_16x16x32_bf16 v[0:3], v[178:181], v[210:213], v[0:3]
	v_mfma_f32_16x16x32_bf16 v[16:19], v[178:181], v[202:205], v[16:19]
	v_mfma_f32_16x16x32_bf16 v[20:23], v[170:173], v[202:205], v[20:23]
	v_mfma_f32_16x16x32_bf16 v[36:39], v[170:173], v[194:197], v[36:39]
	v_mfma_f32_16x16x32_bf16 v[32:35], v[178:181], v[194:197], v[32:35]
	v_mfma_f32_16x16x32_bf16 v[48:51], v[178:181], v[186:189], v[48:51]
	v_mfma_f32_16x16x32_bf16 v[52:55], v[170:173], v[186:189], v[52:55]
	s_setprio 0
	s_barrier
; #define PG8_STAGE(bufoff, gbase, voff) do { const char* _gb = (const char*)(gbase); asm volatile("" : "+s"(_gb));     \
;         _Pragma("unroll") for (int _i = 0; _i < 2; ++_i) \
;         __builtin_amdgcn_global_load_lds((const unsigned*)(_gb + (voff)[_i]), (LAS unsigned*)(lds + (bufoff) + ldsw + _i * 8192), 16, 0, 0); } while (0)
; #define PG8_LDA(dst, b, h) do { _Pragma("unroll") for (int m = 0; m < 4; ++m) _Pragma("unroll") for (int k = 0; k < 2; ++k) dst[m][k] = *(const LAS bf16x8*)(lds + PG8_SA(b, h) + aoff + m * 2048 + k * 1024); } while (0)
; #define PG8_LDB(dst, b, h) do { _Pragma("unroll") for (int n = 0; n < 2; ++n) _Pragma("unroll") for (int k = 0; k < 2; ++k) dst[n][k] = *(const LAS bf16x8*)(lds + PG8_SB(b, h) + boff + n * 2048 + k * 1024); } while (0)
; #define PG8_WAIT_V(n) asm volatile("s_waitcnt vmcnt(" #n ")" ::: "memory")
; #define PG8_WAIT_L(n) asm volatile("s_waitcnt lgkmcnt(" #n ")" ::: "memory")
; #define PG8_BAR __builtin_amdgcn_s_barrier()
; #define PG8_SCHED __builtin_amdgcn_sched_barrier(0)
; template <class Epi>
; __device__ __forceinline__ void gemm_phase(LAS unsigned char* lds, const Gemm g, const StaticOrder& S, const Epi& E) {
;     ...
;             PG8_LDB(B0, 1, 0); PG8_LDB(B1, 1, 1); PG8_SCHED; PG8_LDA(At, 1, 0); PG8_STAGE(PG8_SA(0, 1), a2 + hstepA, voffA);
;             PG8_WAIT_V(8); PG8_WAIT_L(0); PG8_BAR; PG8_MMA2(0, At, B0, B1); PG8_BAR; PG8_SCHED;
;             PG8_LDA(At, 1, 1); PG8_STAGE(PG8_SB(1, 0), b3, voffB); PG8_STAGE(PG8_SB(1, 1), b3 + hstepB, voffB); PG8_STAGE(PG8_SA(1, 0), a3, voffA);
;             PG8_WAIT_V(8); PG8_WAIT_L(0); PG8_BAR; PG8_MMA2(1, At, B0, B1); PG8_BAR; PG8_SCHED;
;         }
	s_add_i32 s68, 0, 0x18000
	v_add_u32_e32 v132, s68, v131
	s_add_i32 s69, 0, 0x1c000
	ds_read_b128 v[150:153], v132
	ds_read_b128 v[154:157], v132 offset:1024
	ds_read_b128 v[158:161], v132 offset:2048
	ds_read_b128 v[162:165], v132 offset:3072
	v_add_u32_e32 v132, s69, v131
	ds_read_b128 v[166:169], v132
	ds_read_b128 v[170:173], v132 offset:1024
	ds_read_b128 v[174:177], v132 offset:2048
	ds_read_b128 v[178:181], v132 offset:3072
	s_add_u32 s50, s50, s20
	s_addc_u32 s51, s51, s21
	s_mov_b32 m0, s27
	ds_read_b128 v[182:185], v145 offset:32768
	ds_read_b128 v[186:189], v145 offset:33792
	ds_read_b128 v[190:193], v145 offset:34816
	ds_read_b128 v[194:197], v145 offset:35840
	ds_read_b128 v[198:201], v145 offset:36864
	ds_read_b128 v[202:205], v145 offset:37888
	ds_read_b128 v[206:209], v145 offset:38912
	ds_read_b128 v[210:213], v145 offset:39936
	s_nop 0
	global_load_lds_dwordx4 v134, s[50:51]
	s_mov_b32 m0, s33
	s_nop 0
	global_load_lds_dwordx4 v130, s[50:51]
	s_waitcnt vmcnt(8)
	s_waitcnt lgkmcnt(0)
	s_barrier
	s_setprio 1
	s_waitcnt lgkmcnt(0)
	v_mfma_f32_16x16x32_bf16 v[124:127], v[150:153], v[182:185], v[124:127]
	v_mfma_f32_16x16x32_bf16 v[120:123], v[158:161], v[182:185], v[120:123]
	v_mfma_f32_16x16x32_bf16 v[104:107], v[158:161], v[190:193], v[104:107]
	v_mfma_f32_16x16x32_bf16 v[108:111], v[150:153], v[190:193], v[108:111]
	v_mfma_f32_16x16x32_bf16 v[92:95], v[150:153], v[198:201], v[92:95]
	v_mfma_f32_16x16x32_bf16 v[88:91], v[158:161], v[198:201], v[88:91]
	v_mfma_f32_16x16x32_bf16 v[72:75], v[158:161], v[206:209], v[72:75]
	v_mfma_f32_16x16x32_bf16 v[76:79], v[150:153], v[206:209], v[76:79]
	v_mfma_f32_16x16x32_bf16 v[68:71], v[166:169], v[206:209], v[68:71]
	v_mfma_f32_16x16x32_bf16 v[64:67], v[174:177], v[206:209], v[64:67]
	v_mfma_f32_16x16x32_bf16 v[80:83], v[174:177], v[198:201], v[80:83]
	v_mfma_f32_16x16x32_bf16 v[84:87], v[166:169], v[198:201], v[84:87]
	v_mfma_f32_16x16x32_bf16 v[100:103], v[166:169], v[190:193], v[100:103]
	v_mfma_f32_16x16x32_bf16 v[96:99], v[174:177], v[190:193], v[96:99]
	v_mfma_f32_16x16x32_bf16 v[112:115], v[174:177], v[182:185], v[112:115]
	v_mfma_f32_16x16x32_bf16 v[116:119], v[166:169], v[182:185], v[116:119]
	v_mfma_f32_16x16x32_bf16 v[124:127], v[154:157], v[186:189], v[124:127]
	v_mfma_f32_16x16x32_bf16 v[120:123], v[162:165], v[186:189], v[120:123]
	v_mfma_f32_16x16x32_bf16 v[104:107], v[162:165], v[194:197], v[104:107]
	v_mfma_f32_16x16x32_bf16 v[108:111], v[154:157], v[194:197], v[108:111]
	v_mfma_f32_16x16x32_bf16 v[92:95], v[154:157], v[202:205], v[92:95]
	v_mfma_f32_16x16x32_bf16 v[88:91], v[162:165], v[202:205], v[88:91]
	v_mfma_f32_16x16x32_bf16 v[72:75], v[162:165], v[210:213], v[72:75]
	v_mfma_f32_16x16x32_bf16 v[76:79], v[154:157], v[210:213], v[76:79]
	v_mfma_f32_16x16x32_bf16 v[68:71], v[170:173], v[210:213], v[68:71]
	v_mfma_f32_16x16x32_bf16 v[64:67], v[178:181], v[210:213], v[64:67]
	v_mfma_f32_16x16x32_bf16 v[80:83], v[178:181], v[202:205], v[80:83]
	v_mfma_f32_16x16x32_bf16 v[84:87], v[170:173], v[202:205], v[84:87]
	v_mfma_f32_16x16x32_bf16 v[100:103], v[170:173], v[194:197], v[100:103]
	v_mfma_f32_16x16x32_bf16 v[96:99], v[178:181], v[194:197], v[96:99]
	v_mfma_f32_16x16x32_bf16 v[112:115], v[178:181], v[186:189], v[112:115]
	v_mfma_f32_16x16x32_bf16 v[116:119], v[170:173], v[186:189], v[116:119]
	s_setprio 0
	s_barrier
	s_add_u32 s48, s48, 0x80
	s_addc_u32 s49, s49, 0
	s_add_i32 s50, s68, s3
	s_mov_b32 m0, s50
	ds_read_b128 v[182:185], v145 offset:49152
	ds_read_b128 v[186:189], v145 offset:50176
	ds_read_b128 v[190:193], v145 offset:51200
	ds_read_b128 v[194:197], v145 offset:52224
	ds_read_b128 v[198:201], v145 offset:53248
	ds_read_b128 v[202:205], v145 offset:54272
	ds_read_b128 v[206:209], v145 offset:55296
	ds_read_b128 v[210:213], v145 offset:56320
	s_nop 0
	global_load_lds_dwordx4 v149, s[48:49]
	s_add_i32 m0, s50, 0x2000
	s_nop 0
	global_load_lds_dwordx4 v128, s[48:49]
	s_add_u32 s48, s52, 0x80
	s_addc_u32 s49, s53, 0
	s_add_i32 s50, s69, s3
	s_mov_b32 m0, s50
	s_nop 0
	global_load_lds_dwordx4 v149, s[48:49]
	s_add_i32 m0, s50, 0x2000
	s_nop 0
	global_load_lds_dwordx4 v128, s[48:49]
	s_mov_b32 m0, s47
	s_nop 0
	global_load_lds_dwordx4 v134, s[6:7]
	s_mov_b32 m0, s54
	s_nop 0
	global_load_lds_dwordx4 v130, s[6:7]
	s_waitcnt vmcnt(8)
	s_waitcnt lgkmcnt(0)
	s_barrier
	s_setprio 1
	s_waitcnt lgkmcnt(0)
	v_mfma_f32_16x16x32_bf16 v[60:63], v[150:153], v[182:185], v[60:63]
	v_mfma_f32_16x16x32_bf16 v[56:59], v[158:161], v[182:185], v[56:59]
	v_mfma_f32_16x16x32_bf16 v[40:43], v[158:161], v[190:193], v[40:43]
	v_mfma_f32_16x16x32_bf16 v[44:47], v[150:153], v[190:193], v[44:47]
	v_mfma_f32_16x16x32_bf16 v[28:31], v[150:153], v[198:201], v[28:31]
	v_mfma_f32_16x16x32_bf16 v[24:27], v[158:161], v[198:201], v[24:27]
	v_mfma_f32_16x16x32_bf16 v[8:11], v[158:161], v[206:209], v[8:11]
	v_mfma_f32_16x16x32_bf16 v[12:15], v[150:153], v[206:209], v[12:15]
	v_mfma_f32_16x16x32_bf16 v[4:7], v[166:169], v[206:209], v[4:7]
	v_mfma_f32_16x16x32_bf16 v[0:3], v[174:177], v[206:209], v[0:3]
	v_mfma_f32_16x16x32_bf16 v[16:19], v[174:177], v[198:201], v[16:19]
	v_mfma_f32_16x16x32_bf16 v[20:23], v[166:169], v[198:201], v[20:23]
	v_mfma_f32_16x16x32_bf16 v[36:39], v[166:169], v[190:193], v[36:39]
	v_mfma_f32_16x16x32_bf16 v[32:35], v[174:177], v[190:193], v[32:35]
	v_mfma_f32_16x16x32_bf16 v[48:51], v[174:177], v[182:185], v[48:51]
	v_mfma_f32_16x16x32_bf16 v[52:55], v[166:169], v[182:185], v[52:55]
	v_mfma_f32_16x16x32_bf16 v[60:63], v[154:157], v[186:189], v[60:63]
	v_mfma_f32_16x16x32_bf16 v[56:59], v[162:165], v[186:189], v[56:59]
	v_mfma_f32_16x16x32_bf16 v[40:43], v[162:165], v[194:197], v[40:43]
	v_mfma_f32_16x16x32_bf16 v[44:47], v[154:157], v[194:197], v[44:47]
	v_mfma_f32_16x16x32_bf16 v[28:31], v[154:157], v[202:205], v[28:31]
	v_mfma_f32_16x16x32_bf16 v[24:27], v[162:165], v[202:205], v[24:27]
	v_mfma_f32_16x16x32_bf16 v[8:11], v[162:165], v[210:213], v[8:11]
	v_mfma_f32_16x16x32_bf16 v[12:15], v[154:157], v[210:213], v[12:15]
	v_mfma_f32_16x16x32_bf16 v[4:7], v[170:173], v[210:213], v[4:7]
	v_mfma_f32_16x16x32_bf16 v[0:3], v[178:181], v[210:213], v[0:3]
	v_mfma_f32_16x16x32_bf16 v[16:19], v[178:181], v[202:205], v[16:19]
	v_mfma_f32_16x16x32_bf16 v[20:23], v[170:173], v[202:205], v[20:23]
	v_mfma_f32_16x16x32_bf16 v[36:39], v[170:173], v[194:197], v[36:39]
	v_mfma_f32_16x16x32_bf16 v[32:35], v[178:181], v[194:197], v[32:35]
	v_mfma_f32_16x16x32_bf16 v[48:51], v[178:181], v[186:189], v[48:51]
	v_mfma_f32_16x16x32_bf16 v[52:55], v[170:173], v[186:189], v[52:55]
	s_setprio 0
	s_barrier
	s_add_i32 s67, s67, 2
	s_add_u32 s63, s63, 0x100
	s_addc_u32 s64, s64, 0
	s_add_u32 s65, s65, 0x100
	s_addc_u32 s66, s66, 0
	s_cmp_gt_u32 s67, 29
	s_cbranch_scc0 .LBB0_109
	s_and_b64 vcc, exec, s[36:37]
	s_cbranch_vccz .LBB0_112
	s_barrier

; #define PG8_STAGE(bufoff, gbase, voff) do { const char* _gb = (const char*)(gbase); asm volatile("" : "+s"(_gb));     \
;         _Pragma("unroll") for (int _i = 0; _i < 2; ++_i) \
;         __builtin_amdgcn_global_load_lds((const unsigned*)(_gb + (voff)[_i]), (LAS unsigned*)(lds + (bufoff) + ldsw + _i * 8192), 16, 0, 0); } while (0)
; #define PG8_LDA(dst, b, h) do { _Pragma("unroll") for (int m = 0; m < 4; ++m) _Pragma("unroll") for (int k = 0; k < 2; ++k) dst[m][k] = *(const LAS bf16x8*)(lds + PG8_SA(b, h) + aoff + m * 2048 + k * 1024); } while (0)
; #define PG8_LDB(dst, b, h) do { _Pragma("unroll") for (int n = 0; n < 2; ++n) _Pragma("unroll") for (int k = 0; k < 2; ++k) dst[n][k] = *(const LAS bf16x8*)(lds + PG8_SB(b, h) + boff + n * 2048 + k * 1024); } while (0)
; #define PG8_WAIT_V(n) asm volatile("s_waitcnt vmcnt(" #n ")" ::: "memory")
; #define PG8_WAIT_L(n) asm volatile("s_waitcnt lgkmcnt(" #n ")" ::: "memory")
; #define PG8_BAR __builtin_amdgcn_s_barrier()
; #define PG8_SCHED __builtin_amdgcn_sched_barrier(0)
; template <class Epi>
; __device__ __forceinline__ void gemm_phase(LAS unsigned char* lds, const Gemm g, const StaticOrder& S, const Epi& E) {
;     ...
;             PG8_LDB(B0, 0, 0); PG8_LDB(B1, 0, 1); PG8_SCHED; PG8_LDA(At, 0, 0); PG8_STAGE(PG8_SA(1, 1), a1 + hstepA, voffA);
;             PG8_WAIT_V(8); PG8_WAIT_L(0); PG8_BAR; PG8_MMA2(0, At, B0, B1); PG8_BAR; PG8_SCHED;
;             PG8_LDA(At, 0, 1); PG8_STAGE(PG8_SB(0, 0), b2, voffB); PG8_STAGE(PG8_SB(0, 1), b2 + hstepB, voffB); PG8_STAGE(PG8_SA(0, 0), a2, voffA);
;             PG8_WAIT_V(8); PG8_WAIT_L(0); PG8_BAR; PG8_MMA2(1, At, B0, B1); PG8_BAR; PG8_SCHED;
.LBB0_230:
	s_waitcnt lgkmcnt(0)
	ds_read_b128 v[128:131], v195
	ds_read_b128 v[132:135], v195 offset:1024
	ds_read_b128 v[136:139], v195 offset:2048
	ds_read_b128 v[140:143], v195 offset:3072
	ds_read_b128 v[144:147], v197
	ds_read_b128 v[148:151], v197 offset:1024
	ds_read_b128 v[152:155], v197 offset:2048
	ds_read_b128 v[156:159], v197 offset:3072
	s_add_i32 s85, s58, 2
	s_cmp_eq_u32 s34, s58
	s_cselect_b32 s62, s14, s83
	s_cselect_b32 s63, s15, s84
	s_cselect_b32 s60, s22, s35
	s_cselect_b32 s61, s23, s82
	s_add_u32 s58, s62, 0x8000
	s_addc_u32 s59, s63, 0
	s_add_u32 s64, s83, s44
	s_addc_u32 s65, s84, s45
	s_add_u32 s64, s64, 0xffff8000
	s_addc_u32 s65, s65, -1
	s_add_i32 m0, s4, 0xc000
	ds_read_b128 v[160:163], v199
	ds_read_b128 v[164:167], v199 offset:1024
	ds_read_b128 v[168:171], v199 offset:2048
	ds_read_b128 v[172:175], v199 offset:3072
	ds_read_b128 v[176:179], v199 offset:4096
	ds_read_b128 v[180:183], v199 offset:5120
	ds_read_b128 v[184:187], v199 offset:6144
	ds_read_b128 v[188:191], v199 offset:7168
	s_nop 0
	global_load_lds_dwordx4 v192, s[64:65]
	s_add_i32 m0, s4, 0xe000
	s_nop 0
	global_load_lds_dwordx4 v196, s[64:65]
	s_waitcnt vmcnt(8)
	s_waitcnt lgkmcnt(0)
	s_barrier
	s_setprio 1
	s_waitcnt lgkmcnt(0)
	v_mfma_f32_16x16x32_bf16 v[124:127], v[128:131], v[160:163], v[124:127]
	v_mfma_f32_16x16x32_bf16 v[120:123], v[136:139], v[160:163], v[120:123]
	v_mfma_f32_16x16x32_bf16 v[112:115], v[136:139], v[168:171], v[112:115]
	v_mfma_f32_16x16x32_bf16 v[116:119], v[128:131], v[168:171], v[116:119]
	v_mfma_f32_16x16x32_bf16 v[108:111], v[128:131], v[176:179], v[108:111]
	v_mfma_f32_16x16x32_bf16 v[104:107], v[136:139], v[176:179], v[104:107]
	v_mfma_f32_16x16x32_bf16 v[96:99], v[136:139], v[184:187], v[96:99]
	v_mfma_f32_16x16x32_bf16 v[100:103], v[128:131], v[184:187], v[100:103]
	v_mfma_f32_16x16x32_bf16 v[68:71], v[144:147], v[184:187], v[68:71]
	v_mfma_f32_16x16x32_bf16 v[64:67], v[152:155], v[184:187], v[64:67]
	v_mfma_f32_16x16x32_bf16 v[72:75], v[152:155], v[176:179], v[72:75]
	v_mfma_f32_16x16x32_bf16 v[76:79], v[144:147], v[176:179], v[76:79]
	v_mfma_f32_16x16x32_bf16 v[84:87], v[144:147], v[168:171], v[84:87]
	v_mfma_f32_16x16x32_bf16 v[80:83], v[152:155], v[168:171], v[80:83]
	v_mfma_f32_16x16x32_bf16 v[88:91], v[152:155], v[160:163], v[88:91]
	v_mfma_f32_16x16x32_bf16 v[92:95], v[144:147], v[160:163], v[92:95]
	v_mfma_f32_16x16x32_bf16 v[124:127], v[132:135], v[164:167], v[124:127]
	v_mfma_f32_16x16x32_bf16 v[120:123], v[140:143], v[164:167], v[120:123]
	v_mfma_f32_16x16x32_bf16 v[112:115], v[140:143], v[172:175], v[112:115]
	v_mfma_f32_16x16x32_bf16 v[116:119], v[132:135], v[172:175], v[116:119]
	v_mfma_f32_16x16x32_bf16 v[108:111], v[132:135], v[180:183], v[108:111]
	v_mfma_f32_16x16x32_bf16 v[104:107], v[140:143], v[180:183], v[104:107]
	v_mfma_f32_16x16x32_bf16 v[96:99], v[140:143], v[188:191], v[96:99]
	v_mfma_f32_16x16x32_bf16 v[100:103], v[132:135], v[188:191], v[100:103]
	v_mfma_f32_16x16x32_bf16 v[68:71], v[148:151], v[188:191], v[68:71]
	v_mfma_f32_16x16x32_bf16 v[64:67], v[156:159], v[188:191], v[64:67]
	v_mfma_f32_16x16x32_bf16 v[72:75], v[156:159], v[180:183], v[72:75]
	v_mfma_f32_16x16x32_bf16 v[76:79], v[148:151], v[180:183], v[76:79]
	v_mfma_f32_16x16x32_bf16 v[84:87], v[148:151], v[172:175], v[84:87]
	v_mfma_f32_16x16x32_bf16 v[80:83], v[156:159], v[172:175], v[80:83]
	v_mfma_f32_16x16x32_bf16 v[88:91], v[156:159], v[164:167], v[88:91]
	v_mfma_f32_16x16x32_bf16 v[92:95], v[148:151], v[164:167], v[92:95]
	s_setprio 0
	s_barrier
	s_add_i32 s86, s70, s3
	s_mov_b64 s[64:65], s[60:61]
	s_mov_b32 m0, s86
	ds_read_b128 v[160:163], v199 offset:16384
	ds_read_b128 v[164:167], v199 offset:17408
	ds_read_b128 v[168:171], v199 offset:18432
	ds_read_b128 v[172:175], v199 offset:19456
	ds_read_b128 v[176:179], v199 offset:20480
	ds_read_b128 v[180:183], v199 offset:21504
	ds_read_b128 v[184:187], v199 offset:22528
	ds_read_b128 v[188:191], v199 offset:23552
	s_nop 0
	global_load_lds_dwordx4 v194, s[64:65]
	s_add_i32 m0, s86, 0x2000
	s_nop 0
	global_load_lds_dwordx4 v198, s[64:65]
	s_add_u32 s64, s60, s40
	s_addc_u32 s65, s61, s41
	s_add_i32 s88, s71, s3
	s_mov_b64 s[86:87], s[64:65]
	s_mov_b32 m0, s88
	s_nop 0
	global_load_lds_dwordx4 v194, s[86:87]
	s_add_i32 m0, s88, 0x2000
	s_nop 0
	global_load_lds_dwordx4 v198, s[86:87]
	s_mov_b64 s[86:87], s[62:63]
	s_mov_b32 m0, s4
	s_nop 0
	global_load_lds_dwordx4 v192, s[86:87]
	s_mov_b32 m0, s5
	s_nop 0
	global_load_lds_dwordx4 v196, s[86:87]
	s_waitcnt vmcnt(8)
	s_waitcnt lgkmcnt(0)
	s_barrier
; #define PG8_STAGE(bufoff, gbase, voff) do { const char* _gb = (const char*)(gbase); asm volatile("" : "+s"(_gb));     \
;         _Pragma("unroll") for (int _i = 0; _i < 2; ++_i) \
;         __builtin_amdgcn_global_load_lds((const unsigned*)(_gb + (voff)[_i]), (LAS unsigned*)(lds + (bufoff) + ldsw + _i * 8192), 16, 0, 0); } while (0)
; #define PG8_LDA(dst, b, h) do { _Pragma("unroll") for (int m = 0; m < 4; ++m) _Pragma("unroll") for (int k = 0; k < 2; ++k) dst[m][k] = *(const LAS bf16x8*)(lds + PG8_SA(b, h) + aoff + m * 2048 + k * 1024); } while (0)
; #define PG8_LDB(dst, b, h) do { _Pragma("unroll") for (int n = 0; n < 2; ++n) _Pragma("unroll") for (int k = 0; k < 2; ++k) dst[n][k] = *(const LAS bf16x8*)(lds + PG8_SB(b, h) + boff + n * 2048 + k * 1024); } while (0)
; #define PG8_WAIT_V(n) asm volatile("s_waitcnt vmcnt(" #n ")" ::: "memory")
; #define PG8_WAIT_L(n) asm volatile("s_waitcnt lgkmcnt(" #n ")" ::: "memory")
; #define PG8_BAR __builtin_amdgcn_s_barrier()
; #define PG8_SCHED __builtin_amdgcn_sched_barrier(0)
; template <class Epi>
; __device__ __forceinline__ void gemm_phase(LAS unsigned char* lds, const Gemm g, const StaticOrder& S, const Epi& E) {
;     ...
;             PG8_WAIT_V(8); PG8_WAIT_L(0); PG8_BAR; PG8_MMA2(1, At, B0, B1); PG8_BAR; PG8_SCHED;
;             PG8_LDB(B0, 1, 0); PG8_LDB(B1, 1, 1); PG8_SCHED; PG8_LDA(At, 1, 0); PG8_STAGE(PG8_SA(0, 1), a2 + hstepA, voffA);
;             PG8_WAIT_V(8); PG8_WAIT_L(0); PG8_BAR; PG8_MMA2(0, At, B0, B1); PG8_BAR; PG8_SCHED;
	s_setprio 1
	s_waitcnt lgkmcnt(0)
	v_mfma_f32_16x16x32_bf16 v[60:63], v[128:131], v[160:163], v[60:63]
	v_mfma_f32_16x16x32_bf16 v[56:59], v[136:139], v[160:163], v[56:59]
	v_mfma_f32_16x16x32_bf16 v[48:51], v[136:139], v[168:171], v[48:51]
	v_mfma_f32_16x16x32_bf16 v[52:55], v[128:131], v[168:171], v[52:55]
	v_mfma_f32_16x16x32_bf16 v[44:47], v[128:131], v[176:179], v[44:47]
	v_mfma_f32_16x16x32_bf16 v[40:43], v[136:139], v[176:179], v[40:43]
	v_mfma_f32_16x16x32_bf16 v[32:35], v[136:139], v[184:187], v[32:35]
	v_mfma_f32_16x16x32_bf16 v[36:39], v[128:131], v[184:187], v[36:39]
	v_mfma_f32_16x16x32_bf16 v[4:7], v[144:147], v[184:187], v[4:7]
	v_mfma_f32_16x16x32_bf16 v[0:3], v[152:155], v[184:187], v[0:3]
	v_mfma_f32_16x16x32_bf16 v[8:11], v[152:155], v[176:179], v[8:11]
	v_mfma_f32_16x16x32_bf16 v[12:15], v[144:147], v[176:179], v[12:15]
	v_mfma_f32_16x16x32_bf16 v[20:23], v[144:147], v[168:171], v[20:23]
	v_mfma_f32_16x16x32_bf16 v[16:19], v[152:155], v[168:171], v[16:19]
	v_mfma_f32_16x16x32_bf16 v[24:27], v[152:155], v[160:163], v[24:27]
	v_mfma_f32_16x16x32_bf16 v[28:31], v[144:147], v[160:163], v[28:31]
	v_mfma_f32_16x16x32_bf16 v[60:63], v[132:135], v[164:167], v[60:63]
	v_mfma_f32_16x16x32_bf16 v[56:59], v[140:143], v[164:167], v[56:59]
	v_mfma_f32_16x16x32_bf16 v[48:51], v[140:143], v[172:175], v[48:51]
	v_mfma_f32_16x16x32_bf16 v[52:55], v[132:135], v[172:175], v[52:55]
	v_mfma_f32_16x16x32_bf16 v[44:47], v[132:135], v[180:183], v[44:47]
	v_mfma_f32_16x16x32_bf16 v[40:43], v[140:143], v[180:183], v[40:43]
	v_mfma_f32_16x16x32_bf16 v[32:35], v[140:143], v[188:191], v[32:35]
	v_mfma_f32_16x16x32_bf16 v[36:39], v[132:135], v[188:191], v[36:39]
	v_mfma_f32_16x16x32_bf16 v[4:7], v[148:151], v[188:191], v[4:7]
	v_mfma_f32_16x16x32_bf16 v[0:3], v[156:159], v[188:191], v[0:3]
	v_mfma_f32_16x16x32_bf16 v[8:11], v[156:159], v[180:183], v[8:11]
	v_mfma_f32_16x16x32_bf16 v[12:15], v[148:151], v[180:183], v[12:15]
	v_mfma_f32_16x16x32_bf16 v[20:23], v[148:151], v[172:175], v[20:23]
	v_mfma_f32_16x16x32_bf16 v[16:19], v[156:159], v[172:175], v[16:19]
	v_mfma_f32_16x16x32_bf16 v[24:27], v[156:159], v[164:167], v[24:27]
	v_mfma_f32_16x16x32_bf16 v[28:31], v[148:151], v[164:167], v[28:31]
	s_setprio 0
	s_barrier
	s_add_i32 s86, 0, 0x18000
	s_add_i32 s87, 0, 0x1c000
	v_add_u32_e32 v140, s86, v217
	v_add_u32_e32 v156, s87, v217
	ds_read_b128 v[128:131], v140
	ds_read_b128 v[132:135], v140 offset:1024
	ds_read_b128 v[136:139], v140 offset:2048
	ds_read_b128 v[140:143], v140 offset:3072
	ds_read_b128 v[144:147], v156
	ds_read_b128 v[148:151], v156 offset:1024
	ds_read_b128 v[152:155], v156 offset:2048
	ds_read_b128 v[156:159], v156 offset:3072
	s_add_u32 s62, s62, s44
	s_addc_u32 s63, s63, s45
	s_mov_b32 m0, s18
	ds_read_b128 v[160:163], v199 offset:32768
	ds_read_b128 v[164:167], v199 offset:33792
	ds_read_b128 v[168:171], v199 offset:34816
	ds_read_b128 v[172:175], v199 offset:35840
	ds_read_b128 v[176:179], v199 offset:36864
	ds_read_b128 v[180:183], v199 offset:37888
	ds_read_b128 v[184:187], v199 offset:38912
	ds_read_b128 v[188:191], v199 offset:39936
	s_nop 0
	global_load_lds_dwordx4 v192, s[62:63]
	s_mov_b32 m0, s19
	s_nop 0
	global_load_lds_dwordx4 v196, s[62:63]
	s_waitcnt vmcnt(8)
	s_waitcnt lgkmcnt(0)
	s_barrier
	s_setprio 1
	s_waitcnt lgkmcnt(0)
	v_mfma_f32_16x16x32_bf16 v[124:127], v[128:131], v[160:163], v[124:127]
	v_mfma_f32_16x16x32_bf16 v[120:123], v[136:139], v[160:163], v[120:123]
	v_mfma_f32_16x16x32_bf16 v[112:115], v[136:139], v[168:171], v[112:115]
	v_mfma_f32_16x16x32_bf16 v[116:119], v[128:131], v[168:171], v[116:119]
	v_mfma_f32_16x16x32_bf16 v[108:111], v[128:131], v[176:179], v[108:111]
	v_mfma_f32_16x16x32_bf16 v[104:107], v[136:139], v[176:179], v[104:107]
	v_mfma_f32_16x16x32_bf16 v[96:99], v[136:139], v[184:187], v[96:99]
	v_mfma_f32_16x16x32_bf16 v[100:103], v[128:131], v[184:187], v[100:103]
	v_mfma_f32_16x16x32_bf16 v[68:71], v[144:147], v[184:187], v[68:71]
	v_mfma_f32_16x16x32_bf16 v[64:67], v[152:155], v[184:187], v[64:67]
	v_mfma_f32_16x16x32_bf16 v[72:75], v[152:155], v[176:179], v[72:75]
	v_mfma_f32_16x16x32_bf16 v[76:79], v[144:147], v[176:179], v[76:79]
	v_mfma_f32_16x16x32_bf16 v[84:87], v[144:147], v[168:171], v[84:87]
	v_mfma_f32_16x16x32_bf16 v[80:83], v[152:155], v[168:171], v[80:83]
	v_mfma_f32_16x16x32_bf16 v[88:91], v[152:155], v[160:163], v[88:91]
	v_mfma_f32_16x16x32_bf16 v[92:95], v[144:147], v[160:163], v[92:95]
	v_mfma_f32_16x16x32_bf16 v[124:127], v[132:135], v[164:167], v[124:127]
	v_mfma_f32_16x16x32_bf16 v[120:123], v[140:143], v[164:167], v[120:123]
	v_mfma_f32_16x16x32_bf16 v[112:115], v[140:143], v[172:175], v[112:115]
	v_mfma_f32_16x16x32_bf16 v[116:119], v[132:135], v[172:175], v[116:119]
	v_mfma_f32_16x16x32_bf16 v[108:111], v[132:135], v[180:183], v[108:111]
	v_mfma_f32_16x16x32_bf16 v[104:107], v[140:143], v[180:183], v[104:107]
	v_mfma_f32_16x16x32_bf16 v[96:99], v[140:143], v[188:191], v[96:99]
	v_mfma_f32_16x16x32_bf16 v[100:103], v[132:135], v[188:191], v[100:103]
	v_mfma_f32_16x16x32_bf16 v[68:71], v[148:151], v[188:191], v[68:71]
	v_mfma_f32_16x16x32_bf16 v[64:67], v[156:159], v[188:191], v[64:67]
	v_mfma_f32_16x16x32_bf16 v[72:75], v[156:159], v[180:183], v[72:75]
	v_mfma_f32_16x16x32_bf16 v[76:79], v[148:151], v[180:183], v[76:79]
	v_mfma_f32_16x16x32_bf16 v[84:87], v[148:151], v[172:175], v[84:87]
	v_mfma_f32_16x16x32_bf16 v[80:83], v[156:159], v[172:175], v[80:83]
	v_mfma_f32_16x16x32_bf16 v[88:91], v[156:159], v[164:167], v[88:91]
	v_mfma_f32_16x16x32_bf16 v[92:95], v[148:151], v[164:167], v[92:95]
	s_setprio 0
	s_barrier
; #define PG8_STAGE(bufoff, gbase, voff) do { const char* _gb = (const char*)(gbase); asm volatile("" : "+s"(_gb));     \
;         _Pragma("unroll") for (int _i = 0; _i < 2; ++_i) \
;         __builtin_amdgcn_global_load_lds((const unsigned*)(_gb + (voff)[_i]), (LAS unsigned*)(lds + (bufoff) + ldsw + _i * 8192), 16, 0, 0); } while (0)
; #define PG8_LDA(dst, b, h) do { _Pragma("unroll") for (int m = 0; m < 4; ++m) _Pragma("unroll") for (int k = 0; k < 2; ++k) dst[m][k] = *(const LAS bf16x8*)(lds + PG8_SA(b, h) + aoff + m * 2048 + k * 1024); } while (0)
; #define PG8_WAIT_V(n) asm volatile("s_waitcnt vmcnt(" #n ")" ::: "memory")
; #define PG8_WAIT_L(n) asm volatile("s_waitcnt lgkmcnt(" #n ")" ::: "memory")
; #define PG8_BAR __builtin_amdgcn_s_barrier()
; #define PG8_SCHED __builtin_amdgcn_sched_barrier(0)
; template <class Epi>
; __device__ __forceinline__ void gemm_phase(LAS unsigned char* lds, const Gemm g, const StaticOrder& S, const Epi& E) {
;     ...
;             PG8_LDA(At, 1, 1); PG8_STAGE(PG8_SB(1, 0), b3, voffB); PG8_STAGE(PG8_SB(1, 1), b3 + hstepB, voffB); PG8_STAGE(PG8_SA(1, 0), a3, voffA);
;             PG8_WAIT_V(8); PG8_WAIT_L(0); PG8_BAR; PG8_MMA2(1, At, B0, B1); PG8_BAR; PG8_SCHED;
;         }
;         if (wr == 0) PG8_BAR;
	s_add_u32 s60, s60, 0x80
	s_addc_u32 s61, s61, 0
	s_add_i32 s62, s86, s3
	s_mov_b32 m0, s62
	ds_read_b128 v[160:163], v199 offset:49152
	ds_read_b128 v[164:167], v199 offset:50176
	ds_read_b128 v[168:171], v199 offset:51200
	ds_read_b128 v[172:175], v199 offset:52224
	ds_read_b128 v[176:179], v199 offset:53248
	ds_read_b128 v[180:183], v199 offset:54272
	ds_read_b128 v[184:187], v199 offset:55296
	ds_read_b128 v[188:191], v199 offset:56320
	s_nop 0
	global_load_lds_dwordx4 v194, s[60:61]
	s_add_i32 m0, s62, 0x2000
	s_nop 0
	global_load_lds_dwordx4 v198, s[60:61]
	s_add_u32 s60, s64, 0x80
	s_addc_u32 s61, s65, 0
	s_add_i32 s62, s87, s3
	s_mov_b32 m0, s62
	s_nop 0
	global_load_lds_dwordx4 v194, s[60:61]
	s_add_i32 m0, s62, 0x2000
	s_nop 0
	global_load_lds_dwordx4 v198, s[60:61]
	s_mov_b32 m0, s25
	s_nop 0
	global_load_lds_dwordx4 v192, s[58:59]
	s_mov_b32 m0, s26
	s_nop 0
	global_load_lds_dwordx4 v196, s[58:59]
	s_waitcnt vmcnt(8)
	s_waitcnt lgkmcnt(0)
	s_barrier
	s_setprio 1
	s_waitcnt lgkmcnt(0)
	v_mfma_f32_16x16x32_bf16 v[60:63], v[128:131], v[160:163], v[60:63]
	v_mfma_f32_16x16x32_bf16 v[56:59], v[136:139], v[160:163], v[56:59]
	v_mfma_f32_16x16x32_bf16 v[48:51], v[136:139], v[168:171], v[48:51]
	v_mfma_f32_16x16x32_bf16 v[52:55], v[128:131], v[168:171], v[52:55]
	v_mfma_f32_16x16x32_bf16 v[44:47], v[128:131], v[176:179], v[44:47]
	v_mfma_f32_16x16x32_bf16 v[40:43], v[136:139], v[176:179], v[40:43]
	v_mfma_f32_16x16x32_bf16 v[32:35], v[136:139], v[184:187], v[32:35]
	v_mfma_f32_16x16x32_bf16 v[36:39], v[128:131], v[184:187], v[36:39]
	v_mfma_f32_16x16x32_bf16 v[4:7], v[144:147], v[184:187], v[4:7]
	v_mfma_f32_16x16x32_bf16 v[0:3], v[152:155], v[184:187], v[0:3]
	v_mfma_f32_16x16x32_bf16 v[8:11], v[152:155], v[176:179], v[8:11]
	v_mfma_f32_16x16x32_bf16 v[12:15], v[144:147], v[176:179], v[12:15]
	v_mfma_f32_16x16x32_bf16 v[20:23], v[144:147], v[168:171], v[20:23]
	v_mfma_f32_16x16x32_bf16 v[16:19], v[152:155], v[168:171], v[16:19]
	v_mfma_f32_16x16x32_bf16 v[24:27], v[152:155], v[160:163], v[24:27]
	v_mfma_f32_16x16x32_bf16 v[28:31], v[144:147], v[160:163], v[28:31]
	v_mfma_f32_16x16x32_bf16 v[60:63], v[132:135], v[164:167], v[60:63]
	v_mfma_f32_16x16x32_bf16 v[56:59], v[140:143], v[164:167], v[56:59]
	v_mfma_f32_16x16x32_bf16 v[48:51], v[140:143], v[172:175], v[48:51]
	v_mfma_f32_16x16x32_bf16 v[52:55], v[132:135], v[172:175], v[52:55]
	v_mfma_f32_16x16x32_bf16 v[44:47], v[132:135], v[180:183], v[44:47]
	v_mfma_f32_16x16x32_bf16 v[40:43], v[140:143], v[180:183], v[40:43]
	v_mfma_f32_16x16x32_bf16 v[32:35], v[140:143], v[188:191], v[32:35]
	v_mfma_f32_16x16x32_bf16 v[36:39], v[132:135], v[188:191], v[36:39]
	v_mfma_f32_16x16x32_bf16 v[4:7], v[148:151], v[188:191], v[4:7]
	v_mfma_f32_16x16x32_bf16 v[0:3], v[156:159], v[188:191], v[0:3]
	v_mfma_f32_16x16x32_bf16 v[8:11], v[156:159], v[180:183], v[8:11]
	v_mfma_f32_16x16x32_bf16 v[12:15], v[148:151], v[180:183], v[12:15]
	v_mfma_f32_16x16x32_bf16 v[20:23], v[148:151], v[172:175], v[20:23]
	v_mfma_f32_16x16x32_bf16 v[16:19], v[156:159], v[172:175], v[16:19]
	v_mfma_f32_16x16x32_bf16 v[24:27], v[156:159], v[164:167], v[24:27]
	v_mfma_f32_16x16x32_bf16 v[28:31], v[148:151], v[164:167], v[28:31]
	s_setprio 0
	s_barrier
	s_add_u32 s35, s35, 0x100
	s_addc_u32 s82, s82, 0
	s_add_u32 s83, s83, 0x10000
	s_addc_u32 s84, s84, 0
	s_cmp_ge_u32 s85, s81
	s_mov_b32 s58, s85
	s_cbranch_scc0 .LBB0_230
	s_and_b64 vcc, exec, s[54:55]
	s_cbranch_vccnz .LBB0_235
	s_cmp_lt_i32 s46, 0
	s_mov_b64 s[34:35], -1
	s_cbranch_scc1 .LBB0_236

; #define PG8_STAGE(bufoff, gbase, voff) do { const char* _gb = (const char*)(gbase); asm volatile("" : "+s"(_gb));     \
;         _Pragma("unroll") for (int _i = 0; _i < 2; ++_i) \
;         __builtin_amdgcn_global_load_lds((const unsigned*)(_gb + (voff)[_i]), (LAS unsigned*)(lds + (bufoff) + ldsw + _i * 8192), 16, 0, 0); } while (0)
; #define PG8_LDA(dst, b, h) do { _Pragma("unroll") for (int m = 0; m < 4; ++m) _Pragma("unroll") for (int k = 0; k < 2; ++k) dst[m][k] = *(const LAS bf16x8*)(lds + PG8_SA(b, h) + aoff + m * 2048 + k * 1024); } while (0)
; #define PG8_LDB(dst, b, h) do { _Pragma("unroll") for (int n = 0; n < 2; ++n) _Pragma("unroll") for (int k = 0; k < 2; ++k) dst[n][k] = *(const LAS bf16x8*)(lds + PG8_SB(b, h) + boff + n * 2048 + k * 1024); } while (0)
; #define PG8_WAIT_V(n) asm volatile("s_waitcnt vmcnt(" #n ")" ::: "memory")
; #define PG8_WAIT_L(n) asm volatile("s_waitcnt lgkmcnt(" #n ")" ::: "memory")
; #define PG8_BAR __builtin_amdgcn_s_barrier()
; #define PG8_SCHED __builtin_amdgcn_sched_barrier(0)
; template <class Epi>
; __device__ __forceinline__ void gemm_phase(LAS unsigned char* lds, const Gemm g, const StaticOrder& S, const Epi& E) {
;     ...
;             PG8_LDB(B0, 0, 0); PG8_LDB(B1, 0, 1); PG8_SCHED; PG8_LDA(At, 0, 0); PG8_STAGE(PG8_SA(1, 1), a1 + hstepA, voffA);
;             PG8_WAIT_V(8); PG8_WAIT_L(0); PG8_BAR; PG8_MMA2(0, At, B0, B1); PG8_BAR; PG8_SCHED;
;             PG8_LDA(At, 0, 1); PG8_STAGE(PG8_SB(0, 0), b2, voffB); PG8_STAGE(PG8_SB(0, 1), b2 + hstepB, voffB); PG8_STAGE(PG8_SA(0, 0), a2, voffA);
;             PG8_WAIT_V(8); PG8_WAIT_L(0); PG8_BAR; PG8_MMA2(1, At, B0, B1); PG8_BAR; PG8_SCHED;
.LBB0_459:
	ds_read_b128 v[128:131], v202
	ds_read_b128 v[132:135], v202 offset:1024
	ds_read_b128 v[136:139], v202 offset:2048
	ds_read_b128 v[140:143], v202 offset:3072
	ds_read_b128 v[144:147], v203
	ds_read_b128 v[166:169], v203 offset:1024
	ds_read_b128 v[170:173], v203 offset:2048
	ds_read_b128 v[174:177], v203 offset:3072
	s_cmp_eq_u32 s68, 28
	s_cselect_b32 s96, s63, vcc_hi
	s_cselect_b32 s97, s18, s81
	s_cselect_b32 s94, s88, s87
	s_cselect_b32 s95, s89, vcc_lo
	s_add_u32 s12, s96, 0x80
	s_addc_u32 s13, s97, 0
	s_add_u32 s34, vcc_hi, s44
	s_addc_u32 s35, s81, s45
	s_add_u32 s34, s34, 0xffffff80
	s_addc_u32 s35, s35, -1
	s_add_i32 m0, s71, 0xc000
	ds_read_b128 v[208:211], v204
	ds_read_b128 v[212:215], v204 offset:1024
	ds_read_b128 v[216:219], v204 offset:2048
	ds_read_b128 v[224:227], v204 offset:3072
	ds_read_b128 v[228:231], v204 offset:4096
	ds_read_b128 v[232:235], v204 offset:5120
	ds_read_b128 v[236:239], v204 offset:6144
	ds_read_b128 v[240:243], v204 offset:7168
	s_nop 0
	global_load_lds_dwordx4 v148, s[34:35]
	s_add_i32 m0, s71, 0xe000
	s_nop 0
	global_load_lds_dwordx4 v152, s[34:35]
	s_waitcnt vmcnt(8)
	s_waitcnt lgkmcnt(0)
	s_barrier
	s_setprio 1
	s_waitcnt lgkmcnt(0)
	v_mfma_f32_16x16x32_bf16 v[124:127], v[128:131], v[208:211], v[124:127]
	v_mfma_f32_16x16x32_bf16 v[120:123], v[136:139], v[208:211], v[120:123]
	v_mfma_f32_16x16x32_bf16 v[104:107], v[136:139], v[216:219], v[104:107]
	v_mfma_f32_16x16x32_bf16 v[108:111], v[128:131], v[216:219], v[108:111]
	v_mfma_f32_16x16x32_bf16 v[92:95], v[128:131], v[228:231], v[92:95]
	v_mfma_f32_16x16x32_bf16 v[88:91], v[136:139], v[228:231], v[88:91]
	v_mfma_f32_16x16x32_bf16 v[72:75], v[136:139], v[236:239], v[72:75]
	v_mfma_f32_16x16x32_bf16 v[76:79], v[128:131], v[236:239], v[76:79]
	v_mfma_f32_16x16x32_bf16 v[68:71], v[144:147], v[236:239], v[68:71]
	v_mfma_f32_16x16x32_bf16 v[64:67], v[170:173], v[236:239], v[64:67]
	v_mfma_f32_16x16x32_bf16 v[80:83], v[170:173], v[228:231], v[80:83]
	v_mfma_f32_16x16x32_bf16 v[84:87], v[144:147], v[228:231], v[84:87]
	v_mfma_f32_16x16x32_bf16 v[100:103], v[144:147], v[216:219], v[100:103]
	v_mfma_f32_16x16x32_bf16 v[96:99], v[170:173], v[216:219], v[96:99]
	v_mfma_f32_16x16x32_bf16 v[112:115], v[170:173], v[208:211], v[112:115]
	v_mfma_f32_16x16x32_bf16 v[116:119], v[144:147], v[208:211], v[116:119]
	v_mfma_f32_16x16x32_bf16 v[124:127], v[132:135], v[212:215], v[124:127]
	v_mfma_f32_16x16x32_bf16 v[120:123], v[140:143], v[212:215], v[120:123]
	v_mfma_f32_16x16x32_bf16 v[104:107], v[140:143], v[224:227], v[104:107]
	v_mfma_f32_16x16x32_bf16 v[108:111], v[132:135], v[224:227], v[108:111]
	v_mfma_f32_16x16x32_bf16 v[92:95], v[132:135], v[232:235], v[92:95]
	v_mfma_f32_16x16x32_bf16 v[88:91], v[140:143], v[232:235], v[88:91]
	v_mfma_f32_16x16x32_bf16 v[72:75], v[140:143], v[240:243], v[72:75]
	v_mfma_f32_16x16x32_bf16 v[76:79], v[132:135], v[240:243], v[76:79]
	v_mfma_f32_16x16x32_bf16 v[68:71], v[166:169], v[240:243], v[68:71]
	v_mfma_f32_16x16x32_bf16 v[64:67], v[174:177], v[240:243], v[64:67]
	v_mfma_f32_16x16x32_bf16 v[80:83], v[174:177], v[232:235], v[80:83]
	v_mfma_f32_16x16x32_bf16 v[84:87], v[166:169], v[232:235], v[84:87]
	v_mfma_f32_16x16x32_bf16 v[100:103], v[166:169], v[224:227], v[100:103]
	v_mfma_f32_16x16x32_bf16 v[96:99], v[174:177], v[224:227], v[96:99]
	v_mfma_f32_16x16x32_bf16 v[112:115], v[174:177], v[212:215], v[112:115]
	v_mfma_f32_16x16x32_bf16 v[116:119], v[166:169], v[212:215], v[116:119]
	s_setprio 0
	s_barrier
	s_add_i32 s58, s5, s3
	s_mov_b64 s[34:35], s[94:95]
	s_mov_b32 m0, s58
	ds_read_b128 v[208:211], v204 offset:16384
	ds_read_b128 v[212:215], v204 offset:17408
	ds_read_b128 v[216:219], v204 offset:18432
	ds_read_b128 v[224:227], v204 offset:19456
	ds_read_b128 v[228:231], v204 offset:20480
	ds_read_b128 v[232:235], v204 offset:21504
	ds_read_b128 v[236:239], v204 offset:22528
	ds_read_b128 v[240:243], v204 offset:23552
	s_nop 0
	global_load_lds_dwordx4 v207, s[34:35]
	s_add_i32 m0, s58, 0x2000
	s_add_u32 s58, s94, s40
	s_addc_u32 s59, s95, s41
	s_add_i32 s69, s25, s3
	global_load_lds_dwordx4 v154, s[34:35]
	s_mov_b64 s[34:35], s[58:59]
	s_mov_b32 m0, s69
	s_nop 0
	global_load_lds_dwordx4 v207, s[34:35]
	s_add_i32 m0, s69, 0x2000
	s_nop 0
	global_load_lds_dwordx4 v154, s[34:35]
	s_mov_b64 s[34:35], s[96:97]
	s_mov_b32 m0, s71
	s_nop 0
	global_load_lds_dwordx4 v148, s[34:35]
	s_mov_b32 m0, s73
	s_nop 0
	global_load_lds_dwordx4 v152, s[34:35]
	s_waitcnt vmcnt(8)
	s_waitcnt lgkmcnt(0)
	s_barrier
	s_setprio 1
	s_waitcnt lgkmcnt(0)
	v_mfma_f32_16x16x32_bf16 v[60:63], v[128:131], v[208:211], v[60:63]
	v_mfma_f32_16x16x32_bf16 v[56:59], v[136:139], v[208:211], v[56:59]
	v_mfma_f32_16x16x32_bf16 v[40:43], v[136:139], v[216:219], v[40:43]
	v_mfma_f32_16x16x32_bf16 v[44:47], v[128:131], v[216:219], v[44:47]
	v_mfma_f32_16x16x32_bf16 v[28:31], v[128:131], v[228:231], v[28:31]
	v_mfma_f32_16x16x32_bf16 v[24:27], v[136:139], v[228:231], v[24:27]
	v_mfma_f32_16x16x32_bf16 v[8:11], v[136:139], v[236:239], v[8:11]
	v_mfma_f32_16x16x32_bf16 v[12:15], v[128:131], v[236:239], v[12:15]
	v_mfma_f32_16x16x32_bf16 v[4:7], v[144:147], v[236:239], v[4:7]
	v_mfma_f32_16x16x32_bf16 v[0:3], v[170:173], v[236:239], v[0:3]
	v_mfma_f32_16x16x32_bf16 v[16:19], v[170:173], v[228:231], v[16:19]
	v_mfma_f32_16x16x32_bf16 v[20:23], v[144:147], v[228:231], v[20:23]
	v_mfma_f32_16x16x32_bf16 v[36:39], v[144:147], v[216:219], v[36:39]
	v_mfma_f32_16x16x32_bf16 v[32:35], v[170:173], v[216:219], v[32:35]
	v_mfma_f32_16x16x32_bf16 v[48:51], v[170:173], v[208:211], v[48:51]
	v_mfma_f32_16x16x32_bf16 v[52:55], v[144:147], v[208:211], v[52:55]
	v_mfma_f32_16x16x32_bf16 v[60:63], v[132:135], v[212:215], v[60:63]
	v_mfma_f32_16x16x32_bf16 v[56:59], v[140:143], v[212:215], v[56:59]
	v_mfma_f32_16x16x32_bf16 v[40:43], v[140:143], v[224:227], v[40:43]
	v_mfma_f32_16x16x32_bf16 v[44:47], v[132:135], v[224:227], v[44:47]
	v_mfma_f32_16x16x32_bf16 v[28:31], v[132:135], v[232:235], v[28:31]
	v_mfma_f32_16x16x32_bf16 v[24:27], v[140:143], v[232:235], v[24:27]
	v_mfma_f32_16x16x32_bf16 v[8:11], v[140:143], v[240:243], v[8:11]
	v_mfma_f32_16x16x32_bf16 v[12:15], v[132:135], v[240:243], v[12:15]
	v_mfma_f32_16x16x32_bf16 v[4:7], v[166:169], v[240:243], v[4:7]
	v_mfma_f32_16x16x32_bf16 v[0:3], v[174:177], v[240:243], v[0:3]
	v_mfma_f32_16x16x32_bf16 v[16:19], v[174:177], v[232:235], v[16:19]
	v_mfma_f32_16x16x32_bf16 v[20:23], v[166:169], v[232:235], v[20:23]
	v_mfma_f32_16x16x32_bf16 v[36:39], v[166:169], v[224:227], v[36:39]
	v_mfma_f32_16x16x32_bf16 v[32:35], v[174:177], v[224:227], v[32:35]
	v_mfma_f32_16x16x32_bf16 v[48:51], v[174:177], v[212:215], v[48:51]
	v_mfma_f32_16x16x32_bf16 v[52:55], v[166:169], v[212:215], v[52:55]
	s_setprio 0
	s_barrier
; #define PG8_STAGE(bufoff, gbase, voff) do { const char* _gb = (const char*)(gbase); asm volatile("" : "+s"(_gb));     \
;         _Pragma("unroll") for (int _i = 0; _i < 2; ++_i) \
;         __builtin_amdgcn_global_load_lds((const unsigned*)(_gb + (voff)[_i]), (LAS unsigned*)(lds + (bufoff) + ldsw + _i * 8192), 16, 0, 0); } while (0)
; #define PG8_LDA(dst, b, h) do { _Pragma("unroll") for (int m = 0; m < 4; ++m) _Pragma("unroll") for (int k = 0; k < 2; ++k) dst[m][k] = *(const LAS bf16x8*)(lds + PG8_SA(b, h) + aoff + m * 2048 + k * 1024); } while (0)
; #define PG8_LDB(dst, b, h) do { _Pragma("unroll") for (int n = 0; n < 2; ++n) _Pragma("unroll") for (int k = 0; k < 2; ++k) dst[n][k] = *(const LAS bf16x8*)(lds + PG8_SB(b, h) + boff + n * 2048 + k * 1024); } while (0)
; #define PG8_WAIT_V(n) asm volatile("s_waitcnt vmcnt(" #n ")" ::: "memory")
; #define PG8_WAIT_L(n) asm volatile("s_waitcnt lgkmcnt(" #n ")" ::: "memory")
; #define PG8_BAR __builtin_amdgcn_s_barrier()
; #define PG8_SCHED __builtin_amdgcn_sched_barrier(0)
; template <class Epi>
; __device__ __forceinline__ void gemm_phase(LAS unsigned char* lds, const Gemm g, const StaticOrder& S, const Epi& E) {
;     ...
;             PG8_LDB(B0, 1, 0); PG8_LDB(B1, 1, 1); PG8_SCHED; PG8_LDA(At, 1, 0); PG8_STAGE(PG8_SA(0, 1), a2 + hstepA, voffA);
;             PG8_WAIT_V(8); PG8_WAIT_L(0); PG8_BAR; PG8_MMA2(0, At, B0, B1); PG8_BAR; PG8_SCHED;
;             PG8_LDA(At, 1, 1); PG8_STAGE(PG8_SB(1, 0), b3, voffB); PG8_STAGE(PG8_SB(1, 1), b3 + hstepB, voffB); PG8_STAGE(PG8_SA(1, 0), a3, voffA);
;             PG8_WAIT_V(8); PG8_WAIT_L(0); PG8_BAR; PG8_MMA2(1, At, B0, B1); PG8_BAR; PG8_SCHED;
;         }
	s_add_i32 s69, 0, 0x18000
	s_add_i32 s27, 0, 0x1c000
	v_add_u32_e32 v140, s69, v181
	v_add_u32_e32 v150, s27, v181
	ds_read_b128 v[128:131], v140
	ds_read_b128 v[132:135], v140 offset:1024
	ds_read_b128 v[136:139], v140 offset:2048
	ds_read_b128 v[140:143], v140 offset:3072
	ds_read_b128 v[144:147], v150
	ds_read_b128 v[166:169], v150 offset:1024
	ds_read_b128 v[170:173], v150 offset:2048
	ds_read_b128 v[174:177], v150 offset:3072
	s_add_u32 s34, s96, s44
	s_addc_u32 s35, s97, s45
	s_mov_b32 m0, s75
	ds_read_b128 v[208:211], v204 offset:32768
	ds_read_b128 v[212:215], v204 offset:33792
	ds_read_b128 v[216:219], v204 offset:34816
	ds_read_b128 v[224:227], v204 offset:35840
	ds_read_b128 v[228:231], v204 offset:36864
	ds_read_b128 v[232:235], v204 offset:37888
	ds_read_b128 v[236:239], v204 offset:38912
	ds_read_b128 v[240:243], v204 offset:39936
	s_nop 0
	global_load_lds_dwordx4 v148, s[34:35]
	s_mov_b32 m0, s77
	s_nop 0
	global_load_lds_dwordx4 v152, s[34:35]
	s_waitcnt vmcnt(8)
	s_waitcnt lgkmcnt(0)
	s_barrier
	s_setprio 1
	s_waitcnt lgkmcnt(0)
	v_mfma_f32_16x16x32_bf16 v[124:127], v[128:131], v[208:211], v[124:127]
	v_mfma_f32_16x16x32_bf16 v[120:123], v[136:139], v[208:211], v[120:123]
	v_mfma_f32_16x16x32_bf16 v[104:107], v[136:139], v[216:219], v[104:107]
	v_mfma_f32_16x16x32_bf16 v[108:111], v[128:131], v[216:219], v[108:111]
	v_mfma_f32_16x16x32_bf16 v[92:95], v[128:131], v[228:231], v[92:95]
	v_mfma_f32_16x16x32_bf16 v[88:91], v[136:139], v[228:231], v[88:91]
	v_mfma_f32_16x16x32_bf16 v[72:75], v[136:139], v[236:239], v[72:75]
	v_mfma_f32_16x16x32_bf16 v[76:79], v[128:131], v[236:239], v[76:79]
	v_mfma_f32_16x16x32_bf16 v[68:71], v[144:147], v[236:239], v[68:71]
	v_mfma_f32_16x16x32_bf16 v[64:67], v[170:173], v[236:239], v[64:67]
	v_mfma_f32_16x16x32_bf16 v[80:83], v[170:173], v[228:231], v[80:83]
	v_mfma_f32_16x16x32_bf16 v[84:87], v[144:147], v[228:231], v[84:87]
	v_mfma_f32_16x16x32_bf16 v[100:103], v[144:147], v[216:219], v[100:103]
	v_mfma_f32_16x16x32_bf16 v[96:99], v[170:173], v[216:219], v[96:99]
	v_mfma_f32_16x16x32_bf16 v[112:115], v[170:173], v[208:211], v[112:115]
	v_mfma_f32_16x16x32_bf16 v[116:119], v[144:147], v[208:211], v[116:119]
	v_mfma_f32_16x16x32_bf16 v[124:127], v[132:135], v[212:215], v[124:127]
	v_mfma_f32_16x16x32_bf16 v[120:123], v[140:143], v[212:215], v[120:123]
	v_mfma_f32_16x16x32_bf16 v[104:107], v[140:143], v[224:227], v[104:107]
	v_mfma_f32_16x16x32_bf16 v[108:111], v[132:135], v[224:227], v[108:111]
	v_mfma_f32_16x16x32_bf16 v[92:95], v[132:135], v[232:235], v[92:95]
	v_mfma_f32_16x16x32_bf16 v[88:91], v[140:143], v[232:235], v[88:91]
	v_mfma_f32_16x16x32_bf16 v[72:75], v[140:143], v[240:243], v[72:75]
	v_mfma_f32_16x16x32_bf16 v[76:79], v[132:135], v[240:243], v[76:79]
	v_mfma_f32_16x16x32_bf16 v[68:71], v[166:169], v[240:243], v[68:71]
	v_mfma_f32_16x16x32_bf16 v[64:67], v[174:177], v[240:243], v[64:67]
	v_mfma_f32_16x16x32_bf16 v[80:83], v[174:177], v[232:235], v[80:83]
	v_mfma_f32_16x16x32_bf16 v[84:87], v[166:169], v[232:235], v[84:87]
	v_mfma_f32_16x16x32_bf16 v[100:103], v[166:169], v[224:227], v[100:103]
	v_mfma_f32_16x16x32_bf16 v[96:99], v[174:177], v[224:227], v[96:99]
	v_mfma_f32_16x16x32_bf16 v[112:115], v[174:177], v[212:215], v[112:115]
	v_mfma_f32_16x16x32_bf16 v[116:119], v[166:169], v[212:215], v[116:119]
	s_setprio 0
	s_barrier
	s_add_u32 s34, s94, 0x80
	s_addc_u32 s35, s95, 0
	s_add_i32 s69, s69, s3
	s_mov_b32 m0, s69
	ds_read_b128 v[208:211], v204 offset:49152
	ds_read_b128 v[212:215], v204 offset:50176
	ds_read_b128 v[216:219], v204 offset:51200
	ds_read_b128 v[224:227], v204 offset:52224
	ds_read_b128 v[228:231], v204 offset:53248
	ds_read_b128 v[232:235], v204 offset:54272
	ds_read_b128 v[236:239], v204 offset:55296
	ds_read_b128 v[240:243], v204 offset:56320
	s_nop 0
	global_load_lds_dwordx4 v207, s[34:35]
	s_add_i32 m0, s69, 0x2000
	s_nop 0
	global_load_lds_dwordx4 v154, s[34:35]
	s_add_u32 s34, s58, 0x80
	s_addc_u32 s35, s59, 0
	s_add_i32 s27, s27, s3
	s_mov_b32 m0, s27
	s_nop 0
	global_load_lds_dwordx4 v207, s[34:35]
	s_add_i32 m0, s27, 0x2000
	s_nop 0
	global_load_lds_dwordx4 v154, s[34:35]
	s_mov_b32 m0, s79
	s_nop 0
	global_load_lds_dwordx4 v148, s[12:13]
	s_mov_b32 m0, s6
	s_nop 0
	global_load_lds_dwordx4 v152, s[12:13]
	s_waitcnt vmcnt(8)
	s_waitcnt lgkmcnt(0)
	s_barrier
	s_setprio 1
	s_waitcnt lgkmcnt(0)
	v_mfma_f32_16x16x32_bf16 v[60:63], v[128:131], v[208:211], v[60:63]
	v_mfma_f32_16x16x32_bf16 v[56:59], v[136:139], v[208:211], v[56:59]
	v_mfma_f32_16x16x32_bf16 v[40:43], v[136:139], v[216:219], v[40:43]
	v_mfma_f32_16x16x32_bf16 v[44:47], v[128:131], v[216:219], v[44:47]
	v_mfma_f32_16x16x32_bf16 v[28:31], v[128:131], v[228:231], v[28:31]
	v_mfma_f32_16x16x32_bf16 v[24:27], v[136:139], v[228:231], v[24:27]
	v_mfma_f32_16x16x32_bf16 v[8:11], v[136:139], v[236:239], v[8:11]
	v_mfma_f32_16x16x32_bf16 v[12:15], v[128:131], v[236:239], v[12:15]
	v_mfma_f32_16x16x32_bf16 v[4:7], v[144:147], v[236:239], v[4:7]
	v_mfma_f32_16x16x32_bf16 v[0:3], v[170:173], v[236:239], v[0:3]
	v_mfma_f32_16x16x32_bf16 v[16:19], v[170:173], v[228:231], v[16:19]
	v_mfma_f32_16x16x32_bf16 v[20:23], v[144:147], v[228:231], v[20:23]
	v_mfma_f32_16x16x32_bf16 v[36:39], v[144:147], v[216:219], v[36:39]
	v_mfma_f32_16x16x32_bf16 v[32:35], v[170:173], v[216:219], v[32:35]
	v_mfma_f32_16x16x32_bf16 v[48:51], v[170:173], v[208:211], v[48:51]
	v_mfma_f32_16x16x32_bf16 v[52:55], v[144:147], v[208:211], v[52:55]
	v_mfma_f32_16x16x32_bf16 v[60:63], v[132:135], v[212:215], v[60:63]
	v_mfma_f32_16x16x32_bf16 v[56:59], v[140:143], v[212:215], v[56:59]
	v_mfma_f32_16x16x32_bf16 v[40:43], v[140:143], v[224:227], v[40:43]
	v_mfma_f32_16x16x32_bf16 v[44:47], v[132:135], v[224:227], v[44:47]
	v_mfma_f32_16x16x32_bf16 v[28:31], v[132:135], v[232:235], v[28:31]
	v_mfma_f32_16x16x32_bf16 v[24:27], v[140:143], v[232:235], v[24:27]
	v_mfma_f32_16x16x32_bf16 v[8:11], v[140:143], v[240:243], v[8:11]
	v_mfma_f32_16x16x32_bf16 v[12:15], v[132:135], v[240:243], v[12:15]
	v_mfma_f32_16x16x32_bf16 v[4:7], v[166:169], v[240:243], v[4:7]
	v_mfma_f32_16x16x32_bf16 v[0:3], v[174:177], v[240:243], v[0:3]
	v_mfma_f32_16x16x32_bf16 v[16:19], v[174:177], v[232:235], v[16:19]
	v_mfma_f32_16x16x32_bf16 v[20:23], v[166:169], v[232:235], v[20:23]
	v_mfma_f32_16x16x32_bf16 v[36:39], v[166:169], v[224:227], v[36:39]
	v_mfma_f32_16x16x32_bf16 v[32:35], v[174:177], v[224:227], v[32:35]
	v_mfma_f32_16x16x32_bf16 v[48:51], v[174:177], v[212:215], v[48:51]
	v_mfma_f32_16x16x32_bf16 v[52:55], v[166:169], v[212:215], v[52:55]
	s_setprio 0
	s_barrier
	s_add_i32 s68, s68, 2
	s_add_u32 s87, s87, 0x100
	s_addc_u32 vcc_lo, vcc_lo, 0
	s_add_u32 vcc_hi, vcc_hi, 0x100
	s_addc_u32 s81, s81, 0
	s_cmp_gt_u32 s68, 29
	s_cbranch_scc0 .LBB0_459
	s_and_b64 vcc, exec, s[54:55]
	s_cbranch_vccz .LBB0_462
	s_barrier

; #define PG8_STAGE(bufoff, gbase, voff) do { const char* _gb = (const char*)(gbase); asm volatile("" : "+s"(_gb));     \
;         _Pragma("unroll") for (int _i = 0; _i < 2; ++_i) \
;         __builtin_amdgcn_global_load_lds((const unsigned*)(_gb + (voff)[_i]), (LAS unsigned*)(lds + (bufoff) + ldsw + _i * 8192), 16, 0, 0); } while (0)
; #define PG8_LDA(dst, b, h) do { _Pragma("unroll") for (int m = 0; m < 4; ++m) _Pragma("unroll") for (int k = 0; k < 2; ++k) dst[m][k] = *(const LAS bf16x8*)(lds + PG8_SA(b, h) + aoff + m * 2048 + k * 1024); } while (0)
; #define PG8_LDB(dst, b, h) do { _Pragma("unroll") for (int n = 0; n < 2; ++n) _Pragma("unroll") for (int k = 0; k < 2; ++k) dst[n][k] = *(const LAS bf16x8*)(lds + PG8_SB(b, h) + boff + n * 2048 + k * 1024); } while (0)
; #define PG8_WAIT_V(n) asm volatile("s_waitcnt vmcnt(" #n ")" ::: "memory")
; #define PG8_WAIT_L(n) asm volatile("s_waitcnt lgkmcnt(" #n ")" ::: "memory")
; #define PG8_BAR __builtin_amdgcn_s_barrier()
; #define PG8_SCHED __builtin_amdgcn_sched_barrier(0)
; template <class Epi>
; __device__ __forceinline__ void gemm_phase(LAS unsigned char* lds, const Gemm g, const StaticOrder& S, const Epi& E) {
;     ...
;             const bool last = (t == nt - 2);
;             const char* a1 = cA + (size_t)(t + 1) * kstepA;
;             const char* a2 = last ? nA : cA + (size_t)(t + 2) * kstepA; const char* b2 = last ? nB : cB + (size_t)(t + 2) * kstepB;
;             const char* a3 = a2 + kstepA; const char* b3 = b2 + kstepB;
;             PG8_LDB(B0, 0, 0); PG8_LDB(B1, 0, 1); PG8_SCHED; PG8_LDA(At, 0, 0); PG8_STAGE(PG8_SA(1, 1), a1 + hstepA, voffA);
;             PG8_WAIT_V(8); PG8_WAIT_L(0); PG8_BAR; PG8_MMA2(0, At, B0, B1); PG8_BAR; PG8_SCHED;
;             PG8_LDA(At, 0, 1); PG8_STAGE(PG8_SB(0, 0), b2, voffB); PG8_STAGE(PG8_SB(0, 1), b2 + hstepB, voffB); PG8_STAGE(PG8_SA(0, 0), a2, voffA);
.LBB0_902:
	s_add_u32 s60, s56, s64
	s_addc_u32 s61, s57, 0
	s_add_u32 s65, s60, 0x100
	s_addc_u32 s66, s61, 0
	s_and_b64 s[60:61], s[62:63], exec
	s_cselect_b32 s69, s11, s66
	s_cselect_b32 s68, s10, s65
	s_add_u32 s60, s54, s64
	s_addc_u32 s61, s55, 0
	s_add_u32 s65, s60, 0x100
	s_addc_u32 s66, s61, 0
	s_add_u32 s60, s68, 0x80
	s_addc_u32 s61, s69, 0
	s_and_b64 s[62:63], s[62:63], exec
	s_cselect_b32 s71, s51, s66
	s_cselect_b32 s70, s50, s65
	s_add_u32 s62, s47, s64
	s_addc_u32 s63, s49, 0
	s_add_u32 s74, s62, 0x80
	s_addc_u32 s75, s63, 0
	s_add_i32 s87, s34, s3
	s_add_i32 m0, s5, 0xc000
	s_add_i32 s88, s5, 0xe000
	s_add_i32 s85, s87, 0x2000
	ds_read_b128 v[128:131], v158
	ds_read_b128 v[132:135], v158 offset:1024
	ds_read_b128 v[136:139], v158 offset:2048
	ds_read_b128 v[140:143], v158 offset:3072
	ds_read_b128 v[162:165], v159
	ds_read_b128 v[166:169], v159 offset:1024
	ds_read_b128 v[170:173], v159 offset:2048
	ds_read_b128 v[174:177], v159 offset:3072
	s_add_u32 s72, s70, s20
	s_addc_u32 s73, s71, s21
	s_add_i32 s86, s35, s3
	s_add_i32 s84, s86, 0x2000
	s_add_i32 s83, 0, 0x18000
	s_add_i32 s82, 0, 0x1c000
	s_add_u32 s66, s68, s36
	s_addc_u32 s67, s69, s37
	s_add_u32 s64, s70, 0x80
	s_addc_u32 s65, s71, 0
	s_add_i32 s81, s83, s3
	s_add_i32 s80, s81, 0x2000
	s_add_u32 s62, s72, 0x80
	s_addc_u32 s63, s73, 0
	s_add_i32 s79, s82, s3
	s_add_i32 s78, s79, 0x2000
	ds_read_b128 v[178:181], v160
	ds_read_b128 v[182:185], v160 offset:1024
	ds_read_b128 v[186:189], v160 offset:2048
	ds_read_b128 v[190:193], v160 offset:3072
	ds_read_b128 v[194:197], v160 offset:4096
	ds_read_b128 v[198:201], v160 offset:5120
	ds_read_b128 v[202:205], v160 offset:6144
	ds_read_b128 v[206:209], v160 offset:7168
	s_nop 0
	global_load_lds_dwordx4 v150, s[74:75]
	s_mov_b32 m0, s88
	s_nop 0
	global_load_lds_dwordx4 v146, s[74:75]
	s_waitcnt vmcnt(8)
	s_waitcnt lgkmcnt(0)
	s_barrier
	s_setprio 1
	s_waitcnt lgkmcnt(0)
	v_mfma_f32_16x16x32_bf16 v[124:127], v[128:131], v[178:181], v[124:127]
	v_mfma_f32_16x16x32_bf16 v[120:123], v[136:139], v[178:181], v[120:123]
	v_mfma_f32_16x16x32_bf16 v[104:107], v[136:139], v[186:189], v[104:107]
	v_mfma_f32_16x16x32_bf16 v[108:111], v[128:131], v[186:189], v[108:111]
	v_mfma_f32_16x16x32_bf16 v[96:99], v[128:131], v[194:197], v[96:99]
	v_mfma_f32_16x16x32_bf16 v[88:91], v[136:139], v[194:197], v[88:91]
	v_mfma_f32_16x16x32_bf16 v[72:75], v[136:139], v[202:205], v[72:75]
	v_mfma_f32_16x16x32_bf16 v[80:83], v[128:131], v[202:205], v[80:83]
	v_mfma_f32_16x16x32_bf16 v[68:71], v[162:165], v[202:205], v[68:71]
	v_mfma_f32_16x16x32_bf16 v[64:67], v[170:173], v[202:205], v[64:67]
	v_mfma_f32_16x16x32_bf16 v[76:79], v[170:173], v[194:197], v[76:79]
	v_mfma_f32_16x16x32_bf16 v[84:87], v[162:165], v[194:197], v[84:87]
	v_mfma_f32_16x16x32_bf16 v[100:103], v[162:165], v[186:189], v[100:103]
	v_mfma_f32_16x16x32_bf16 v[92:95], v[170:173], v[186:189], v[92:95]
	v_mfma_f32_16x16x32_bf16 v[112:115], v[170:173], v[178:181], v[112:115]
	v_mfma_f32_16x16x32_bf16 v[116:119], v[162:165], v[178:181], v[116:119]
	v_mfma_f32_16x16x32_bf16 v[124:127], v[132:135], v[182:185], v[124:127]
	v_mfma_f32_16x16x32_bf16 v[120:123], v[140:143], v[182:185], v[120:123]
	v_mfma_f32_16x16x32_bf16 v[104:107], v[140:143], v[190:193], v[104:107]
	v_mfma_f32_16x16x32_bf16 v[108:111], v[132:135], v[190:193], v[108:111]
	v_mfma_f32_16x16x32_bf16 v[96:99], v[132:135], v[198:201], v[96:99]
	v_mfma_f32_16x16x32_bf16 v[88:91], v[140:143], v[198:201], v[88:91]
	v_mfma_f32_16x16x32_bf16 v[72:75], v[140:143], v[206:209], v[72:75]
	v_mfma_f32_16x16x32_bf16 v[80:83], v[132:135], v[206:209], v[80:83]
	v_mfma_f32_16x16x32_bf16 v[68:71], v[166:169], v[206:209], v[68:71]
	v_mfma_f32_16x16x32_bf16 v[64:67], v[174:177], v[206:209], v[64:67]
	v_mfma_f32_16x16x32_bf16 v[76:79], v[174:177], v[198:201], v[76:79]
	v_mfma_f32_16x16x32_bf16 v[84:87], v[166:169], v[198:201], v[84:87]
	v_mfma_f32_16x16x32_bf16 v[100:103], v[166:169], v[190:193], v[100:103]
	v_mfma_f32_16x16x32_bf16 v[92:95], v[174:177], v[190:193], v[92:95]
	v_mfma_f32_16x16x32_bf16 v[112:115], v[174:177], v[182:185], v[112:115]
	v_mfma_f32_16x16x32_bf16 v[116:119], v[166:169], v[182:185], v[116:119]
	s_setprio 0
	s_barrier
	s_mov_b32 m0, s87
	ds_read_b128 v[178:181], v160 offset:16384
	ds_read_b128 v[182:185], v160 offset:17408
	ds_read_b128 v[186:189], v160 offset:18432
	ds_read_b128 v[190:193], v160 offset:19456
	ds_read_b128 v[194:197], v160 offset:20480
	ds_read_b128 v[198:201], v160 offset:21504
	ds_read_b128 v[202:205], v160 offset:22528
	ds_read_b128 v[206:209], v160 offset:23552
	s_nop 0
	global_load_lds_dwordx4 v161, s[70:71]
	s_mov_b32 m0, s85
	s_nop 0
	global_load_lds_dwordx4 v144, s[70:71]
	s_mov_b32 m0, s86
	s_nop 0
	global_load_lds_dwordx4 v161, s[72:73]
	s_mov_b32 m0, s84
	s_nop 0
	global_load_lds_dwordx4 v144, s[72:73]
	s_mov_b32 m0, s5
	s_nop 0
	global_load_lds_dwordx4 v150, s[68:69]
	s_mov_b32 m0, s6
	s_nop 0
	global_load_lds_dwordx4 v146, s[68:69]
	s_waitcnt vmcnt(8)
	s_waitcnt lgkmcnt(0)
	s_barrier
; #define PG8_STAGE(bufoff, gbase, voff) do { const char* _gb = (const char*)(gbase); asm volatile("" : "+s"(_gb));     \
;         _Pragma("unroll") for (int _i = 0; _i < 2; ++_i) \
;         __builtin_amdgcn_global_load_lds((const unsigned*)(_gb + (voff)[_i]), (LAS unsigned*)(lds + (bufoff) + ldsw + _i * 8192), 16, 0, 0); } while (0)
; #define PG8_LDA(dst, b, h) do { _Pragma("unroll") for (int m = 0; m < 4; ++m) _Pragma("unroll") for (int k = 0; k < 2; ++k) dst[m][k] = *(const LAS bf16x8*)(lds + PG8_SA(b, h) + aoff + m * 2048 + k * 1024); } while (0)
; #define PG8_LDB(dst, b, h) do { _Pragma("unroll") for (int n = 0; n < 2; ++n) _Pragma("unroll") for (int k = 0; k < 2; ++k) dst[n][k] = *(const LAS bf16x8*)(lds + PG8_SB(b, h) + boff + n * 2048 + k * 1024); } while (0)
; #define PG8_WAIT_V(n) asm volatile("s_waitcnt vmcnt(" #n ")" ::: "memory")
; #define PG8_WAIT_L(n) asm volatile("s_waitcnt lgkmcnt(" #n ")" ::: "memory")
; #define PG8_BAR __builtin_amdgcn_s_barrier()
; #define PG8_SCHED __builtin_amdgcn_sched_barrier(0)
; template <class Epi>
; __device__ __forceinline__ void gemm_phase(LAS unsigned char* lds, const Gemm g, const StaticOrder& S, const Epi& E) {
;     ...
;             PG8_WAIT_V(8); PG8_WAIT_L(0); PG8_BAR; PG8_MMA2(1, At, B0, B1); PG8_BAR; PG8_SCHED;
;             PG8_LDB(B0, 1, 0); PG8_LDB(B1, 1, 1); PG8_SCHED; PG8_LDA(At, 1, 0); PG8_STAGE(PG8_SA(0, 1), a2 + hstepA, voffA);
;             PG8_WAIT_V(8); PG8_WAIT_L(0); PG8_BAR; PG8_MMA2(0, At, B0, B1); PG8_BAR; PG8_SCHED;
	s_setprio 1
	s_waitcnt lgkmcnt(0)
	v_mfma_f32_16x16x32_bf16 v[60:63], v[128:131], v[178:181], v[60:63]
	v_mfma_f32_16x16x32_bf16 v[56:59], v[136:139], v[178:181], v[56:59]
	v_mfma_f32_16x16x32_bf16 v[40:43], v[136:139], v[186:189], v[40:43]
	v_mfma_f32_16x16x32_bf16 v[48:51], v[128:131], v[186:189], v[48:51]
	v_mfma_f32_16x16x32_bf16 v[32:35], v[128:131], v[194:197], v[32:35]
	v_mfma_f32_16x16x32_bf16 v[24:27], v[136:139], v[194:197], v[24:27]
	v_mfma_f32_16x16x32_bf16 v[8:11], v[136:139], v[202:205], v[8:11]
	v_mfma_f32_16x16x32_bf16 v[16:19], v[128:131], v[202:205], v[16:19]
	v_mfma_f32_16x16x32_bf16 v[4:7], v[162:165], v[202:205], v[4:7]
	v_mfma_f32_16x16x32_bf16 v[0:3], v[170:173], v[202:205], v[0:3]
	v_mfma_f32_16x16x32_bf16 v[12:15], v[170:173], v[194:197], v[12:15]
	v_mfma_f32_16x16x32_bf16 v[20:23], v[162:165], v[194:197], v[20:23]
	v_mfma_f32_16x16x32_bf16 v[36:39], v[162:165], v[186:189], v[36:39]
	v_mfma_f32_16x16x32_bf16 v[28:31], v[170:173], v[186:189], v[28:31]
	v_mfma_f32_16x16x32_bf16 v[44:47], v[170:173], v[178:181], v[44:47]
	v_mfma_f32_16x16x32_bf16 v[52:55], v[162:165], v[178:181], v[52:55]
	v_mfma_f32_16x16x32_bf16 v[60:63], v[132:135], v[182:185], v[60:63]
	v_mfma_f32_16x16x32_bf16 v[56:59], v[140:143], v[182:185], v[56:59]
	v_mfma_f32_16x16x32_bf16 v[40:43], v[140:143], v[190:193], v[40:43]
	v_mfma_f32_16x16x32_bf16 v[48:51], v[132:135], v[190:193], v[48:51]
	v_mfma_f32_16x16x32_bf16 v[32:35], v[132:135], v[198:201], v[32:35]
	v_mfma_f32_16x16x32_bf16 v[24:27], v[140:143], v[198:201], v[24:27]
	v_mfma_f32_16x16x32_bf16 v[8:11], v[140:143], v[206:209], v[8:11]
	v_mfma_f32_16x16x32_bf16 v[16:19], v[132:135], v[206:209], v[16:19]
	v_mfma_f32_16x16x32_bf16 v[4:7], v[166:169], v[206:209], v[4:7]
	v_mfma_f32_16x16x32_bf16 v[0:3], v[174:177], v[206:209], v[0:3]
	v_mfma_f32_16x16x32_bf16 v[12:15], v[174:177], v[198:201], v[12:15]
	v_mfma_f32_16x16x32_bf16 v[20:23], v[166:169], v[198:201], v[20:23]
	v_mfma_f32_16x16x32_bf16 v[36:39], v[166:169], v[190:193], v[36:39]
	v_mfma_f32_16x16x32_bf16 v[28:31], v[174:177], v[190:193], v[28:31]
	v_mfma_f32_16x16x32_bf16 v[44:47], v[174:177], v[182:185], v[44:47]
	v_mfma_f32_16x16x32_bf16 v[52:55], v[166:169], v[182:185], v[52:55]
	s_setprio 0
	s_barrier
	v_add_u32_e32 v140, s83, v147
	v_add_u32_e32 v148, s82, v147
	ds_read_b128 v[128:131], v140
	ds_read_b128 v[132:135], v140 offset:1024
	ds_read_b128 v[136:139], v140 offset:2048
	ds_read_b128 v[140:143], v140 offset:3072
	ds_read_b128 v[162:165], v148
	ds_read_b128 v[166:169], v148 offset:1024
	ds_read_b128 v[170:173], v148 offset:2048
	ds_read_b128 v[174:177], v148 offset:3072
	s_mov_b32 m0, s7
	ds_read_b128 v[178:181], v160 offset:32768
	ds_read_b128 v[182:185], v160 offset:33792
	ds_read_b128 v[186:189], v160 offset:34816
	ds_read_b128 v[190:193], v160 offset:35840
	ds_read_b128 v[194:197], v160 offset:36864
	ds_read_b128 v[198:201], v160 offset:37888
	ds_read_b128 v[202:205], v160 offset:38912
	ds_read_b128 v[206:209], v160 offset:39936
	s_nop 0
	global_load_lds_dwordx4 v150, s[66:67]
	s_mov_b32 m0, s18
	s_nop 0
	global_load_lds_dwordx4 v146, s[66:67]
	s_waitcnt vmcnt(8)
	s_waitcnt lgkmcnt(0)
	s_barrier
	s_setprio 1
	s_waitcnt lgkmcnt(0)
	v_mfma_f32_16x16x32_bf16 v[124:127], v[128:131], v[178:181], v[124:127]
	v_mfma_f32_16x16x32_bf16 v[120:123], v[136:139], v[178:181], v[120:123]
	v_mfma_f32_16x16x32_bf16 v[104:107], v[136:139], v[186:189], v[104:107]
	v_mfma_f32_16x16x32_bf16 v[108:111], v[128:131], v[186:189], v[108:111]
	v_mfma_f32_16x16x32_bf16 v[96:99], v[128:131], v[194:197], v[96:99]
	v_mfma_f32_16x16x32_bf16 v[88:91], v[136:139], v[194:197], v[88:91]
	v_mfma_f32_16x16x32_bf16 v[72:75], v[136:139], v[202:205], v[72:75]
	v_mfma_f32_16x16x32_bf16 v[80:83], v[128:131], v[202:205], v[80:83]
	v_mfma_f32_16x16x32_bf16 v[68:71], v[162:165], v[202:205], v[68:71]
	v_mfma_f32_16x16x32_bf16 v[64:67], v[170:173], v[202:205], v[64:67]
	v_mfma_f32_16x16x32_bf16 v[76:79], v[170:173], v[194:197], v[76:79]
	v_mfma_f32_16x16x32_bf16 v[84:87], v[162:165], v[194:197], v[84:87]
	v_mfma_f32_16x16x32_bf16 v[100:103], v[162:165], v[186:189], v[100:103]
	v_mfma_f32_16x16x32_bf16 v[92:95], v[170:173], v[186:189], v[92:95]
	v_mfma_f32_16x16x32_bf16 v[112:115], v[170:173], v[178:181], v[112:115]
	v_mfma_f32_16x16x32_bf16 v[116:119], v[162:165], v[178:181], v[116:119]
	v_mfma_f32_16x16x32_bf16 v[124:127], v[132:135], v[182:185], v[124:127]
	v_mfma_f32_16x16x32_bf16 v[120:123], v[140:143], v[182:185], v[120:123]
	v_mfma_f32_16x16x32_bf16 v[104:107], v[140:143], v[190:193], v[104:107]
	v_mfma_f32_16x16x32_bf16 v[108:111], v[132:135], v[190:193], v[108:111]
	v_mfma_f32_16x16x32_bf16 v[96:99], v[132:135], v[198:201], v[96:99]
	v_mfma_f32_16x16x32_bf16 v[88:91], v[140:143], v[198:201], v[88:91]
	v_mfma_f32_16x16x32_bf16 v[72:75], v[140:143], v[206:209], v[72:75]
	v_mfma_f32_16x16x32_bf16 v[80:83], v[132:135], v[206:209], v[80:83]
	v_mfma_f32_16x16x32_bf16 v[68:71], v[166:169], v[206:209], v[68:71]
	v_mfma_f32_16x16x32_bf16 v[64:67], v[174:177], v[206:209], v[64:67]
	v_mfma_f32_16x16x32_bf16 v[76:79], v[174:177], v[198:201], v[76:79]
	v_mfma_f32_16x16x32_bf16 v[84:87], v[166:169], v[198:201], v[84:87]
	v_mfma_f32_16x16x32_bf16 v[100:103], v[166:169], v[190:193], v[100:103]
	v_mfma_f32_16x16x32_bf16 v[92:95], v[174:177], v[190:193], v[92:95]
	v_mfma_f32_16x16x32_bf16 v[112:115], v[174:177], v[182:185], v[112:115]
	v_mfma_f32_16x16x32_bf16 v[116:119], v[166:169], v[182:185], v[116:119]
	s_setprio 0
	s_barrier
; #define PG8_STAGE(bufoff, gbase, voff) do { const char* _gb = (const char*)(gbase); asm volatile("" : "+s"(_gb));     \
;         _Pragma("unroll") for (int _i = 0; _i < 2; ++_i) \
;         __builtin_amdgcn_global_load_lds((const unsigned*)(_gb + (voff)[_i]), (LAS unsigned*)(lds + (bufoff) + ldsw + _i * 8192), 16, 0, 0); } while (0)
; #define PG8_LDA(dst, b, h) do { _Pragma("unroll") for (int m = 0; m < 4; ++m) _Pragma("unroll") for (int k = 0; k < 2; ++k) dst[m][k] = *(const LAS bf16x8*)(lds + PG8_SA(b, h) + aoff + m * 2048 + k * 1024); } while (0)
; #define PG8_WAIT_V(n) asm volatile("s_waitcnt vmcnt(" #n ")" ::: "memory")
; #define PG8_WAIT_L(n) asm volatile("s_waitcnt lgkmcnt(" #n ")" ::: "memory")
; #define PG8_BAR __builtin_amdgcn_s_barrier()
; #define PG8_SCHED __builtin_amdgcn_sched_barrier(0)
; template <class Epi>
; __device__ __forceinline__ void gemm_phase(LAS unsigned char* lds, const Gemm g, const StaticOrder& S, const Epi& E) {
;     ...
;             PG8_LDA(At, 1, 1); PG8_STAGE(PG8_SB(1, 0), b3, voffB); PG8_STAGE(PG8_SB(1, 1), b3 + hstepB, voffB); PG8_STAGE(PG8_SA(1, 0), a3, voffA);
;             PG8_WAIT_V(8); PG8_WAIT_L(0); PG8_BAR; PG8_MMA2(1, At, B0, B1); PG8_BAR; PG8_SCHED;
;         }
;         if (wr == 0) PG8_BAR;
	s_mov_b32 m0, s81
	ds_read_b128 v[178:181], v160 offset:49152
	ds_read_b128 v[182:185], v160 offset:50176
	ds_read_b128 v[186:189], v160 offset:51200
	ds_read_b128 v[190:193], v160 offset:52224
	ds_read_b128 v[194:197], v160 offset:53248
	ds_read_b128 v[198:201], v160 offset:54272
	ds_read_b128 v[202:205], v160 offset:55296
	ds_read_b128 v[206:209], v160 offset:56320
	s_nop 0
	global_load_lds_dwordx4 v161, s[64:65]
	s_mov_b32 m0, s80
	s_nop 0
	global_load_lds_dwordx4 v144, s[64:65]
	s_mov_b32 m0, s79
	s_nop 0
	global_load_lds_dwordx4 v161, s[62:63]
	s_mov_b32 m0, s78
	s_nop 0
	global_load_lds_dwordx4 v144, s[62:63]
	s_mov_b32 m0, s25
	s_nop 0
	global_load_lds_dwordx4 v150, s[60:61]
	s_mov_b32 m0, s26
	s_nop 0
	global_load_lds_dwordx4 v146, s[60:61]
	s_waitcnt vmcnt(8)
	s_waitcnt lgkmcnt(0)
	s_barrier
	s_setprio 1
	s_waitcnt lgkmcnt(0)
	v_mfma_f32_16x16x32_bf16 v[60:63], v[128:131], v[178:181], v[60:63]
	v_mfma_f32_16x16x32_bf16 v[56:59], v[136:139], v[178:181], v[56:59]
	v_mfma_f32_16x16x32_bf16 v[40:43], v[136:139], v[186:189], v[40:43]
	v_mfma_f32_16x16x32_bf16 v[48:51], v[128:131], v[186:189], v[48:51]
	v_mfma_f32_16x16x32_bf16 v[32:35], v[128:131], v[194:197], v[32:35]
	v_mfma_f32_16x16x32_bf16 v[24:27], v[136:139], v[194:197], v[24:27]
	v_mfma_f32_16x16x32_bf16 v[8:11], v[136:139], v[202:205], v[8:11]
	v_mfma_f32_16x16x32_bf16 v[16:19], v[128:131], v[202:205], v[16:19]
	v_mfma_f32_16x16x32_bf16 v[4:7], v[162:165], v[202:205], v[4:7]
	v_mfma_f32_16x16x32_bf16 v[0:3], v[170:173], v[202:205], v[0:3]
	v_mfma_f32_16x16x32_bf16 v[12:15], v[170:173], v[194:197], v[12:15]
	v_mfma_f32_16x16x32_bf16 v[20:23], v[162:165], v[194:197], v[20:23]
	v_mfma_f32_16x16x32_bf16 v[36:39], v[162:165], v[186:189], v[36:39]
	v_mfma_f32_16x16x32_bf16 v[28:31], v[170:173], v[186:189], v[28:31]
	v_mfma_f32_16x16x32_bf16 v[44:47], v[170:173], v[178:181], v[44:47]
	v_mfma_f32_16x16x32_bf16 v[52:55], v[162:165], v[178:181], v[52:55]
	v_mfma_f32_16x16x32_bf16 v[60:63], v[132:135], v[182:185], v[60:63]
	v_mfma_f32_16x16x32_bf16 v[56:59], v[140:143], v[182:185], v[56:59]
	v_mfma_f32_16x16x32_bf16 v[40:43], v[140:143], v[190:193], v[40:43]
	v_mfma_f32_16x16x32_bf16 v[48:51], v[132:135], v[190:193], v[48:51]
	v_mfma_f32_16x16x32_bf16 v[32:35], v[132:135], v[198:201], v[32:35]
	v_mfma_f32_16x16x32_bf16 v[24:27], v[140:143], v[198:201], v[24:27]
	v_mfma_f32_16x16x32_bf16 v[8:11], v[140:143], v[206:209], v[8:11]
	v_mfma_f32_16x16x32_bf16 v[16:19], v[132:135], v[206:209], v[16:19]
	v_mfma_f32_16x16x32_bf16 v[4:7], v[166:169], v[206:209], v[4:7]
	v_mfma_f32_16x16x32_bf16 v[0:3], v[174:177], v[206:209], v[0:3]
	v_mfma_f32_16x16x32_bf16 v[12:15], v[174:177], v[198:201], v[12:15]
	v_mfma_f32_16x16x32_bf16 v[20:23], v[166:169], v[198:201], v[20:23]
	v_mfma_f32_16x16x32_bf16 v[36:39], v[166:169], v[190:193], v[36:39]
	v_mfma_f32_16x16x32_bf16 v[28:31], v[174:177], v[190:193], v[28:31]
	v_mfma_f32_16x16x32_bf16 v[44:47], v[174:177], v[182:185], v[44:47]
	v_mfma_f32_16x16x32_bf16 v[52:55], v[166:169], v[182:185], v[52:55]
	s_setprio 0
	s_barrier
	s_movk_i32 s64, 0x100
	s_andn2_b64 vcc, exec, s[58:59]
	s_mov_b64 s[62:63], -1
	s_mov_b64 s[58:59], 0
	s_cbranch_vccz .LBB0_902
	s_and_b64 vcc, exec, s[42:43]
	s_cbranch_vccz .LBB0_905
	s_barrier

; #define PG8_STAGE(bufoff, gbase, voff) do { const char* _gb = (const char*)(gbase); asm volatile("" : "+s"(_gb));     \
;         _Pragma("unroll") for (int _i = 0; _i < 2; ++_i) \
;         __builtin_amdgcn_global_load_lds((const unsigned*)(_gb + (voff)[_i]), (LAS unsigned*)(lds + (bufoff) + ldsw + _i * 8192), 16, 0, 0); } while (0)
; #define PG8_LDA(dst, b, h) do { _Pragma("unroll") for (int m = 0; m < 4; ++m) _Pragma("unroll") for (int k = 0; k < 2; ++k) dst[m][k] = *(const LAS bf16x8*)(lds + PG8_SA(b, h) + aoff + m * 2048 + k * 1024); } while (0)
; #define PG8_LDB(dst, b, h) do { _Pragma("unroll") for (int n = 0; n < 2; ++n) _Pragma("unroll") for (int k = 0; k < 2; ++k) dst[n][k] = *(const LAS bf16x8*)(lds + PG8_SB(b, h) + boff + n * 2048 + k * 1024); } while (0)
; #define PG8_WAIT_V(n) asm volatile("s_waitcnt vmcnt(" #n ")" ::: "memory")
; #define PG8_WAIT_L(n) asm volatile("s_waitcnt lgkmcnt(" #n ")" ::: "memory")
; #define PG8_BAR __builtin_amdgcn_s_barrier()
; #define PG8_SCHED __builtin_amdgcn_sched_barrier(0)
; template <class Epi>
; __device__ __forceinline__ void gemm_phase(LAS unsigned char* lds, const Gemm g, const StaticOrder& S, const Epi& E) {
;     ...
;             const bool last = (t == nt - 2);
;             const char* a1 = cA + (size_t)(t + 1) * kstepA;
;             const char* a2 = last ? nA : cA + (size_t)(t + 2) * kstepA; const char* b2 = last ? nB : cB + (size_t)(t + 2) * kstepB;
;             const char* a3 = a2 + kstepA; const char* b3 = b2 + kstepB;
;             PG8_LDB(B0, 0, 0); PG8_LDB(B1, 0, 1); PG8_SCHED; PG8_LDA(At, 0, 0); PG8_STAGE(PG8_SA(1, 1), a1 + hstepA, voffA);
;             PG8_WAIT_V(8); PG8_WAIT_L(0); PG8_BAR; PG8_MMA2(0, At, B0, B1); PG8_BAR; PG8_SCHED;
;             PG8_LDA(At, 0, 1); PG8_STAGE(PG8_SB(0, 0), b2, voffB); PG8_STAGE(PG8_SB(0, 1), b2 + hstepB, voffB); PG8_STAGE(PG8_SA(0, 0), a2, voffA);
.LBB0_980:
	s_waitcnt lgkmcnt(0)
	ds_read_b128 v[128:131], v195
	ds_read_b128 v[132:135], v195 offset:1024
	ds_read_b128 v[136:139], v195 offset:2048
	ds_read_b128 v[140:143], v195 offset:3072
	ds_read_b128 v[144:147], v197
	ds_read_b128 v[148:151], v197 offset:1024
	ds_read_b128 v[152:155], v197 offset:2048
	ds_read_b128 v[156:159], v197 offset:3072
	s_add_i32 s85, s34, 2
	s_cmp_eq_u32 s80, s34
	s_cselect_b32 s64, s79, s83
	s_cselect_b32 s65, s15, s84
	s_cselect_b32 s62, s54, s81
	s_cselect_b32 s63, s55, s82
	s_add_u32 s60, s64, 0x80
	s_addc_u32 s61, s65, 0
	s_add_u32 s34, s83, s40
	s_addc_u32 s35, s84, s41
	s_add_u32 s34, s34, 0xffffff80
	s_addc_u32 s35, s35, -1
	s_add_i32 m0, s4, 0xc000
	ds_read_b128 v[160:163], v199
	ds_read_b128 v[164:167], v199 offset:1024
	ds_read_b128 v[168:171], v199 offset:2048
	ds_read_b128 v[172:175], v199 offset:3072
	ds_read_b128 v[176:179], v199 offset:4096
	ds_read_b128 v[180:183], v199 offset:5120
	ds_read_b128 v[184:187], v199 offset:6144
	ds_read_b128 v[188:191], v199 offset:7168
	s_nop 0
	global_load_lds_dwordx4 v192, s[34:35]
	s_add_i32 m0, s4, 0xe000
	s_nop 0
	global_load_lds_dwordx4 v196, s[34:35]
	s_waitcnt vmcnt(8)
	s_waitcnt lgkmcnt(0)
	s_barrier
	s_setprio 1
	s_waitcnt lgkmcnt(0)
	v_mfma_f32_16x16x32_bf16 v[124:127], v[128:131], v[160:163], v[124:127]
	v_mfma_f32_16x16x32_bf16 v[120:123], v[136:139], v[160:163], v[120:123]
	v_mfma_f32_16x16x32_bf16 v[112:115], v[136:139], v[168:171], v[112:115]
	v_mfma_f32_16x16x32_bf16 v[116:119], v[128:131], v[168:171], v[116:119]
	v_mfma_f32_16x16x32_bf16 v[108:111], v[128:131], v[176:179], v[108:111]
	v_mfma_f32_16x16x32_bf16 v[104:107], v[136:139], v[176:179], v[104:107]
	v_mfma_f32_16x16x32_bf16 v[96:99], v[136:139], v[184:187], v[96:99]
	v_mfma_f32_16x16x32_bf16 v[100:103], v[128:131], v[184:187], v[100:103]
	v_mfma_f32_16x16x32_bf16 v[68:71], v[144:147], v[184:187], v[68:71]
	v_mfma_f32_16x16x32_bf16 v[64:67], v[152:155], v[184:187], v[64:67]
	v_mfma_f32_16x16x32_bf16 v[72:75], v[152:155], v[176:179], v[72:75]
	v_mfma_f32_16x16x32_bf16 v[76:79], v[144:147], v[176:179], v[76:79]
	v_mfma_f32_16x16x32_bf16 v[84:87], v[144:147], v[168:171], v[84:87]
	v_mfma_f32_16x16x32_bf16 v[80:83], v[152:155], v[168:171], v[80:83]
	v_mfma_f32_16x16x32_bf16 v[88:91], v[152:155], v[160:163], v[88:91]
	v_mfma_f32_16x16x32_bf16 v[92:95], v[144:147], v[160:163], v[92:95]
	v_mfma_f32_16x16x32_bf16 v[124:127], v[132:135], v[164:167], v[124:127]
	v_mfma_f32_16x16x32_bf16 v[120:123], v[140:143], v[164:167], v[120:123]
	v_mfma_f32_16x16x32_bf16 v[112:115], v[140:143], v[172:175], v[112:115]
	v_mfma_f32_16x16x32_bf16 v[116:119], v[132:135], v[172:175], v[116:119]
	v_mfma_f32_16x16x32_bf16 v[108:111], v[132:135], v[180:183], v[108:111]
	v_mfma_f32_16x16x32_bf16 v[104:107], v[140:143], v[180:183], v[104:107]
	v_mfma_f32_16x16x32_bf16 v[96:99], v[140:143], v[188:191], v[96:99]
	v_mfma_f32_16x16x32_bf16 v[100:103], v[132:135], v[188:191], v[100:103]
	v_mfma_f32_16x16x32_bf16 v[68:71], v[148:151], v[188:191], v[68:71]
	v_mfma_f32_16x16x32_bf16 v[64:67], v[156:159], v[188:191], v[64:67]
	v_mfma_f32_16x16x32_bf16 v[72:75], v[156:159], v[180:183], v[72:75]
	v_mfma_f32_16x16x32_bf16 v[76:79], v[148:151], v[180:183], v[76:79]
	v_mfma_f32_16x16x32_bf16 v[84:87], v[148:151], v[172:175], v[84:87]
	v_mfma_f32_16x16x32_bf16 v[80:83], v[156:159], v[172:175], v[80:83]
	v_mfma_f32_16x16x32_bf16 v[88:91], v[156:159], v[164:167], v[88:91]
	v_mfma_f32_16x16x32_bf16 v[92:95], v[148:151], v[164:167], v[92:95]
	s_setprio 0
	s_barrier
	s_add_i32 s86, s69, s3
	s_mov_b64 s[34:35], s[62:63]
	s_mov_b32 m0, s86
	ds_read_b128 v[160:163], v199 offset:16384
	ds_read_b128 v[164:167], v199 offset:17408
	ds_read_b128 v[168:171], v199 offset:18432
	ds_read_b128 v[172:175], v199 offset:19456
	ds_read_b128 v[176:179], v199 offset:20480
	ds_read_b128 v[180:183], v199 offset:21504
	ds_read_b128 v[184:187], v199 offset:22528
	ds_read_b128 v[188:191], v199 offset:23552
	s_nop 0
	global_load_lds_dwordx4 v194, s[34:35]
	s_add_i32 m0, s86, 0x2000
	s_nop 0
	global_load_lds_dwordx4 v198, s[34:35]
	s_add_u32 s34, s62, s36
	s_addc_u32 s35, s63, s37
	s_add_i32 s88, s70, s3
	s_mov_b64 s[86:87], s[34:35]
	s_mov_b32 m0, s88
	s_nop 0
	global_load_lds_dwordx4 v194, s[86:87]
	s_add_i32 m0, s88, 0x2000
	s_nop 0
	global_load_lds_dwordx4 v198, s[86:87]
	s_mov_b64 s[86:87], s[64:65]
	s_mov_b32 m0, s4
	s_nop 0
	global_load_lds_dwordx4 v192, s[86:87]
	s_mov_b32 m0, s5
	s_nop 0
	global_load_lds_dwordx4 v196, s[86:87]
	s_waitcnt vmcnt(8)
	s_waitcnt lgkmcnt(0)
	s_barrier
; #define PG8_STAGE(bufoff, gbase, voff) do { const char* _gb = (const char*)(gbase); asm volatile("" : "+s"(_gb));     \
;         _Pragma("unroll") for (int _i = 0; _i < 2; ++_i) \
;         __builtin_amdgcn_global_load_lds((const unsigned*)(_gb + (voff)[_i]), (LAS unsigned*)(lds + (bufoff) + ldsw + _i * 8192), 16, 0, 0); } while (0)
; #define PG8_LDA(dst, b, h) do { _Pragma("unroll") for (int m = 0; m < 4; ++m) _Pragma("unroll") for (int k = 0; k < 2; ++k) dst[m][k] = *(const LAS bf16x8*)(lds + PG8_SA(b, h) + aoff + m * 2048 + k * 1024); } while (0)
; #define PG8_LDB(dst, b, h) do { _Pragma("unroll") for (int n = 0; n < 2; ++n) _Pragma("unroll") for (int k = 0; k < 2; ++k) dst[n][k] = *(const LAS bf16x8*)(lds + PG8_SB(b, h) + boff + n * 2048 + k * 1024); } while (0)
; #define PG8_WAIT_V(n) asm volatile("s_waitcnt vmcnt(" #n ")" ::: "memory")
; #define PG8_WAIT_L(n) asm volatile("s_waitcnt lgkmcnt(" #n ")" ::: "memory")
; #define PG8_BAR __builtin_amdgcn_s_barrier()
; #define PG8_SCHED __builtin_amdgcn_sched_barrier(0)
; template <class Epi>
; __device__ __forceinline__ void gemm_phase(LAS unsigned char* lds, const Gemm g, const StaticOrder& S, const Epi& E) {
;     ...
;             PG8_WAIT_V(8); PG8_WAIT_L(0); PG8_BAR; PG8_MMA2(1, At, B0, B1); PG8_BAR; PG8_SCHED;
;             PG8_LDB(B0, 1, 0); PG8_LDB(B1, 1, 1); PG8_SCHED; PG8_LDA(At, 1, 0); PG8_STAGE(PG8_SA(0, 1), a2 + hstepA, voffA);
;             PG8_WAIT_V(8); PG8_WAIT_L(0); PG8_BAR; PG8_MMA2(0, At, B0, B1); PG8_BAR; PG8_SCHED;
	s_setprio 1
	s_waitcnt lgkmcnt(0)
	v_mfma_f32_16x16x32_bf16 v[60:63], v[128:131], v[160:163], v[60:63]
	v_mfma_f32_16x16x32_bf16 v[56:59], v[136:139], v[160:163], v[56:59]
	v_mfma_f32_16x16x32_bf16 v[48:51], v[136:139], v[168:171], v[48:51]
	v_mfma_f32_16x16x32_bf16 v[52:55], v[128:131], v[168:171], v[52:55]
	v_mfma_f32_16x16x32_bf16 v[44:47], v[128:131], v[176:179], v[44:47]
	v_mfma_f32_16x16x32_bf16 v[40:43], v[136:139], v[176:179], v[40:43]
	v_mfma_f32_16x16x32_bf16 v[32:35], v[136:139], v[184:187], v[32:35]
	v_mfma_f32_16x16x32_bf16 v[36:39], v[128:131], v[184:187], v[36:39]
	v_mfma_f32_16x16x32_bf16 v[4:7], v[144:147], v[184:187], v[4:7]
	v_mfma_f32_16x16x32_bf16 v[0:3], v[152:155], v[184:187], v[0:3]
	v_mfma_f32_16x16x32_bf16 v[8:11], v[152:155], v[176:179], v[8:11]
	v_mfma_f32_16x16x32_bf16 v[12:15], v[144:147], v[176:179], v[12:15]
	v_mfma_f32_16x16x32_bf16 v[20:23], v[144:147], v[168:171], v[20:23]
	v_mfma_f32_16x16x32_bf16 v[16:19], v[152:155], v[168:171], v[16:19]
	v_mfma_f32_16x16x32_bf16 v[24:27], v[152:155], v[160:163], v[24:27]
	v_mfma_f32_16x16x32_bf16 v[28:31], v[144:147], v[160:163], v[28:31]
	v_mfma_f32_16x16x32_bf16 v[60:63], v[132:135], v[164:167], v[60:63]
	v_mfma_f32_16x16x32_bf16 v[56:59], v[140:143], v[164:167], v[56:59]
	v_mfma_f32_16x16x32_bf16 v[48:51], v[140:143], v[172:175], v[48:51]
	v_mfma_f32_16x16x32_bf16 v[52:55], v[132:135], v[172:175], v[52:55]
	v_mfma_f32_16x16x32_bf16 v[44:47], v[132:135], v[180:183], v[44:47]
	v_mfma_f32_16x16x32_bf16 v[40:43], v[140:143], v[180:183], v[40:43]
	v_mfma_f32_16x16x32_bf16 v[32:35], v[140:143], v[188:191], v[32:35]
	v_mfma_f32_16x16x32_bf16 v[36:39], v[132:135], v[188:191], v[36:39]
	v_mfma_f32_16x16x32_bf16 v[4:7], v[148:151], v[188:191], v[4:7]
	v_mfma_f32_16x16x32_bf16 v[0:3], v[156:159], v[188:191], v[0:3]
	v_mfma_f32_16x16x32_bf16 v[8:11], v[156:159], v[180:183], v[8:11]
	v_mfma_f32_16x16x32_bf16 v[12:15], v[148:151], v[180:183], v[12:15]
	v_mfma_f32_16x16x32_bf16 v[20:23], v[148:151], v[172:175], v[20:23]
	v_mfma_f32_16x16x32_bf16 v[16:19], v[156:159], v[172:175], v[16:19]
	v_mfma_f32_16x16x32_bf16 v[24:27], v[156:159], v[164:167], v[24:27]
	v_mfma_f32_16x16x32_bf16 v[28:31], v[148:151], v[164:167], v[28:31]
	s_setprio 0
	s_barrier
	s_add_i32 s86, 0, 0x18000
	s_add_i32 s87, 0, 0x1c000
	v_add_u32_e32 v140, s86, v224
	v_add_u32_e32 v156, s87, v224
	ds_read_b128 v[128:131], v140
	ds_read_b128 v[132:135], v140 offset:1024
	ds_read_b128 v[136:139], v140 offset:2048
	ds_read_b128 v[140:143], v140 offset:3072
	ds_read_b128 v[144:147], v156
	ds_read_b128 v[148:151], v156 offset:1024
	ds_read_b128 v[152:155], v156 offset:2048
	ds_read_b128 v[156:159], v156 offset:3072
	s_add_u32 s64, s64, s40
	s_addc_u32 s65, s65, s41
	s_mov_b32 m0, s6
	ds_read_b128 v[160:163], v199 offset:32768
	ds_read_b128 v[164:167], v199 offset:33792
	ds_read_b128 v[168:171], v199 offset:34816
	ds_read_b128 v[172:175], v199 offset:35840
	ds_read_b128 v[176:179], v199 offset:36864
	ds_read_b128 v[180:183], v199 offset:37888
	ds_read_b128 v[184:187], v199 offset:38912
	ds_read_b128 v[188:191], v199 offset:39936
	s_nop 0
	global_load_lds_dwordx4 v192, s[64:65]
	s_mov_b32 m0, s7
	s_nop 0
	global_load_lds_dwordx4 v196, s[64:65]
	s_waitcnt vmcnt(8)
	s_waitcnt lgkmcnt(0)
	s_barrier
	s_setprio 1
	s_waitcnt lgkmcnt(0)
	v_mfma_f32_16x16x32_bf16 v[124:127], v[128:131], v[160:163], v[124:127]
	v_mfma_f32_16x16x32_bf16 v[120:123], v[136:139], v[160:163], v[120:123]
	v_mfma_f32_16x16x32_bf16 v[112:115], v[136:139], v[168:171], v[112:115]
	v_mfma_f32_16x16x32_bf16 v[116:119], v[128:131], v[168:171], v[116:119]
	v_mfma_f32_16x16x32_bf16 v[108:111], v[128:131], v[176:179], v[108:111]
	v_mfma_f32_16x16x32_bf16 v[104:107], v[136:139], v[176:179], v[104:107]
	v_mfma_f32_16x16x32_bf16 v[96:99], v[136:139], v[184:187], v[96:99]
	v_mfma_f32_16x16x32_bf16 v[100:103], v[128:131], v[184:187], v[100:103]
	v_mfma_f32_16x16x32_bf16 v[68:71], v[144:147], v[184:187], v[68:71]
	v_mfma_f32_16x16x32_bf16 v[64:67], v[152:155], v[184:187], v[64:67]
	v_mfma_f32_16x16x32_bf16 v[72:75], v[152:155], v[176:179], v[72:75]
	v_mfma_f32_16x16x32_bf16 v[76:79], v[144:147], v[176:179], v[76:79]
	v_mfma_f32_16x16x32_bf16 v[84:87], v[144:147], v[168:171], v[84:87]
	v_mfma_f32_16x16x32_bf16 v[80:83], v[152:155], v[168:171], v[80:83]
	v_mfma_f32_16x16x32_bf16 v[88:91], v[152:155], v[160:163], v[88:91]
	v_mfma_f32_16x16x32_bf16 v[92:95], v[144:147], v[160:163], v[92:95]
	v_mfma_f32_16x16x32_bf16 v[124:127], v[132:135], v[164:167], v[124:127]
	v_mfma_f32_16x16x32_bf16 v[120:123], v[140:143], v[164:167], v[120:123]
	v_mfma_f32_16x16x32_bf16 v[112:115], v[140:143], v[172:175], v[112:115]
	v_mfma_f32_16x16x32_bf16 v[116:119], v[132:135], v[172:175], v[116:119]
	v_mfma_f32_16x16x32_bf16 v[108:111], v[132:135], v[180:183], v[108:111]
	v_mfma_f32_16x16x32_bf16 v[104:107], v[140:143], v[180:183], v[104:107]
	v_mfma_f32_16x16x32_bf16 v[96:99], v[140:143], v[188:191], v[96:99]
	v_mfma_f32_16x16x32_bf16 v[100:103], v[132:135], v[188:191], v[100:103]
	v_mfma_f32_16x16x32_bf16 v[68:71], v[148:151], v[188:191], v[68:71]
	v_mfma_f32_16x16x32_bf16 v[64:67], v[156:159], v[188:191], v[64:67]
	v_mfma_f32_16x16x32_bf16 v[72:75], v[156:159], v[180:183], v[72:75]
	v_mfma_f32_16x16x32_bf16 v[76:79], v[148:151], v[180:183], v[76:79]
	v_mfma_f32_16x16x32_bf16 v[84:87], v[148:151], v[172:175], v[84:87]
	v_mfma_f32_16x16x32_bf16 v[80:83], v[156:159], v[172:175], v[80:83]
	v_mfma_f32_16x16x32_bf16 v[88:91], v[156:159], v[164:167], v[88:91]
	v_mfma_f32_16x16x32_bf16 v[92:95], v[148:151], v[164:167], v[92:95]
	s_setprio 0
	s_barrier
; #define PG8_STAGE(bufoff, gbase, voff) do { const char* _gb = (const char*)(gbase); asm volatile("" : "+s"(_gb));     \
;         _Pragma("unroll") for (int _i = 0; _i < 2; ++_i) \
;         __builtin_amdgcn_global_load_lds((const unsigned*)(_gb + (voff)[_i]), (LAS unsigned*)(lds + (bufoff) + ldsw + _i * 8192), 16, 0, 0); } while (0)
; #define PG8_LDA(dst, b, h) do { _Pragma("unroll") for (int m = 0; m < 4; ++m) _Pragma("unroll") for (int k = 0; k < 2; ++k) dst[m][k] = *(const LAS bf16x8*)(lds + PG8_SA(b, h) + aoff + m * 2048 + k * 1024); } while (0)
; #define PG8_WAIT_V(n) asm volatile("s_waitcnt vmcnt(" #n ")" ::: "memory")
; #define PG8_WAIT_L(n) asm volatile("s_waitcnt lgkmcnt(" #n ")" ::: "memory")
; #define PG8_BAR __builtin_amdgcn_s_barrier()
; #define PG8_SCHED __builtin_amdgcn_sched_barrier(0)
; template <class Epi>
; __device__ __forceinline__ void gemm_phase(LAS unsigned char* lds, const Gemm g, const StaticOrder& S, const Epi& E) {
;     ...
;             PG8_LDA(At, 1, 1); PG8_STAGE(PG8_SB(1, 0), b3, voffB); PG8_STAGE(PG8_SB(1, 1), b3 + hstepB, voffB); PG8_STAGE(PG8_SA(1, 0), a3, voffA);
;             PG8_WAIT_V(8); PG8_WAIT_L(0); PG8_BAR; PG8_MMA2(1, At, B0, B1); PG8_BAR; PG8_SCHED;
;         }
;         if (wr == 0) PG8_BAR;
	s_add_u32 s62, s62, 0x80
	s_addc_u32 s63, s63, 0
	s_add_i32 s64, s86, s3
	s_mov_b32 m0, s64
	ds_read_b128 v[160:163], v199 offset:49152
	ds_read_b128 v[164:167], v199 offset:50176
	ds_read_b128 v[168:171], v199 offset:51200
	ds_read_b128 v[172:175], v199 offset:52224
	ds_read_b128 v[176:179], v199 offset:53248
	ds_read_b128 v[180:183], v199 offset:54272
	ds_read_b128 v[184:187], v199 offset:55296
	ds_read_b128 v[188:191], v199 offset:56320
	s_nop 0
	global_load_lds_dwordx4 v194, s[62:63]
	s_add_i32 m0, s64, 0x2000
	s_add_u32 s34, s34, 0x80
	global_load_lds_dwordx4 v198, s[62:63]
	s_addc_u32 s35, s35, 0
	s_add_i32 s62, s87, s3
	s_mov_b32 m0, s62
	s_nop 0
	global_load_lds_dwordx4 v194, s[34:35]
	s_add_i32 m0, s62, 0x2000
	s_nop 0
	global_load_lds_dwordx4 v198, s[34:35]
	s_mov_b32 m0, s18
	s_nop 0
	global_load_lds_dwordx4 v192, s[60:61]
	s_mov_b32 m0, s19
	s_nop 0
	global_load_lds_dwordx4 v196, s[60:61]
	s_waitcnt vmcnt(8)
	s_waitcnt lgkmcnt(0)
	s_barrier
	s_setprio 1
	s_waitcnt lgkmcnt(0)
	v_mfma_f32_16x16x32_bf16 v[60:63], v[128:131], v[160:163], v[60:63]
	v_mfma_f32_16x16x32_bf16 v[56:59], v[136:139], v[160:163], v[56:59]
	v_mfma_f32_16x16x32_bf16 v[48:51], v[136:139], v[168:171], v[48:51]
	v_mfma_f32_16x16x32_bf16 v[52:55], v[128:131], v[168:171], v[52:55]
	v_mfma_f32_16x16x32_bf16 v[44:47], v[128:131], v[176:179], v[44:47]
	v_mfma_f32_16x16x32_bf16 v[40:43], v[136:139], v[176:179], v[40:43]
	v_mfma_f32_16x16x32_bf16 v[32:35], v[136:139], v[184:187], v[32:35]
	v_mfma_f32_16x16x32_bf16 v[36:39], v[128:131], v[184:187], v[36:39]
	v_mfma_f32_16x16x32_bf16 v[4:7], v[144:147], v[184:187], v[4:7]
	v_mfma_f32_16x16x32_bf16 v[0:3], v[152:155], v[184:187], v[0:3]
	v_mfma_f32_16x16x32_bf16 v[8:11], v[152:155], v[176:179], v[8:11]
	v_mfma_f32_16x16x32_bf16 v[12:15], v[144:147], v[176:179], v[12:15]
	v_mfma_f32_16x16x32_bf16 v[20:23], v[144:147], v[168:171], v[20:23]
	v_mfma_f32_16x16x32_bf16 v[16:19], v[152:155], v[168:171], v[16:19]
	v_mfma_f32_16x16x32_bf16 v[24:27], v[152:155], v[160:163], v[24:27]
	v_mfma_f32_16x16x32_bf16 v[28:31], v[144:147], v[160:163], v[28:31]
	v_mfma_f32_16x16x32_bf16 v[60:63], v[132:135], v[164:167], v[60:63]
	v_mfma_f32_16x16x32_bf16 v[56:59], v[140:143], v[164:167], v[56:59]
	v_mfma_f32_16x16x32_bf16 v[48:51], v[140:143], v[172:175], v[48:51]
	v_mfma_f32_16x16x32_bf16 v[52:55], v[132:135], v[172:175], v[52:55]
	v_mfma_f32_16x16x32_bf16 v[44:47], v[132:135], v[180:183], v[44:47]
	v_mfma_f32_16x16x32_bf16 v[40:43], v[140:143], v[180:183], v[40:43]
	v_mfma_f32_16x16x32_bf16 v[32:35], v[140:143], v[188:191], v[32:35]
	v_mfma_f32_16x16x32_bf16 v[36:39], v[132:135], v[188:191], v[36:39]
	v_mfma_f32_16x16x32_bf16 v[4:7], v[148:151], v[188:191], v[4:7]
	v_mfma_f32_16x16x32_bf16 v[0:3], v[156:159], v[188:191], v[0:3]
	v_mfma_f32_16x16x32_bf16 v[8:11], v[156:159], v[180:183], v[8:11]
	v_mfma_f32_16x16x32_bf16 v[12:15], v[148:151], v[180:183], v[12:15]
	v_mfma_f32_16x16x32_bf16 v[20:23], v[148:151], v[172:175], v[20:23]
	v_mfma_f32_16x16x32_bf16 v[16:19], v[156:159], v[172:175], v[16:19]
	v_mfma_f32_16x16x32_bf16 v[24:27], v[156:159], v[164:167], v[24:27]
	v_mfma_f32_16x16x32_bf16 v[28:31], v[148:151], v[164:167], v[28:31]
	s_setprio 0
	s_barrier
	s_add_u32 s81, s81, 0x100
	s_addc_u32 s82, s82, 0
	s_add_u32 s83, s83, 0x100
	s_addc_u32 s84, s84, 0
	s_cmp_ge_u32 s85, s78
	s_mov_b32 s34, s85
	s_cbranch_scc0 .LBB0_980
	s_and_b64 vcc, exec, s[50:51]
	s_cbranch_vccnz .LBB0_985
	s_cmp_lt_i32 s42, 0
	s_mov_b64 s[34:35], -1
	s_cbranch_scc1 .LBB0_986

; #define PG8_STAGE(bufoff, gbase, voff) do { const char* _gb = (const char*)(gbase); asm volatile("" : "+s"(_gb));     \
;         _Pragma("unroll") for (int _i = 0; _i < 2; ++_i) \
;         __builtin_amdgcn_global_load_lds((const unsigned*)(_gb + (voff)[_i]), (LAS unsigned*)(lds + (bufoff) + ldsw + _i * 8192), 16, 0, 0); } while (0)
; #define PG8_LDA(dst, b, h) do { _Pragma("unroll") for (int m = 0; m < 4; ++m) _Pragma("unroll") for (int k = 0; k < 2; ++k) dst[m][k] = *(const LAS bf16x8*)(lds + PG8_SA(b, h) + aoff + m * 2048 + k * 1024); } while (0)
; #define PG8_LDB(dst, b, h) do { _Pragma("unroll") for (int n = 0; n < 2; ++n) _Pragma("unroll") for (int k = 0; k < 2; ++k) dst[n][k] = *(const LAS bf16x8*)(lds + PG8_SB(b, h) + boff + n * 2048 + k * 1024); } while (0)
; #define PG8_WAIT_V(n) asm volatile("s_waitcnt vmcnt(" #n ")" ::: "memory")
; #define PG8_WAIT_L(n) asm volatile("s_waitcnt lgkmcnt(" #n ")" ::: "memory")
; #define PG8_BAR __builtin_amdgcn_s_barrier()
; #define PG8_SCHED __builtin_amdgcn_sched_barrier(0)
; template <class Epi>
; __device__ __forceinline__ void gemm_phase(LAS unsigned char* lds, const Gemm g, const StaticOrder& S, const Epi& E) {
;     ...
;             const bool last = (t == nt - 2);
;             const char* a1 = cA + (size_t)(t + 1) * kstepA;
;             const char* a2 = last ? nA : cA + (size_t)(t + 2) * kstepA; const char* b2 = last ? nB : cB + (size_t)(t + 2) * kstepB;
;             const char* a3 = a2 + kstepA; const char* b3 = b2 + kstepB;
;             PG8_LDB(B0, 0, 0); PG8_LDB(B1, 0, 1); PG8_SCHED; PG8_LDA(At, 0, 0); PG8_STAGE(PG8_SA(1, 1), a1 + hstepA, voffA);
;             PG8_WAIT_V(8); PG8_WAIT_L(0); PG8_BAR; PG8_MMA2(0, At, B0, B1); PG8_BAR; PG8_SCHED;
;             PG8_LDA(At, 0, 1); PG8_STAGE(PG8_SB(0, 0), b2, voffB); PG8_STAGE(PG8_SB(0, 1), b2 + hstepB, voffB); PG8_STAGE(PG8_SA(0, 0), a2, voffA);
;             PG8_WAIT_V(8); PG8_WAIT_L(0); PG8_BAR; PG8_MMA2(1, At, B0, B1); PG8_BAR; PG8_SCHED;
.LBB0_1207:
	ds_read_b128 v[150:153], v135
	ds_read_b128 v[154:157], v135 offset:1024
	ds_read_b128 v[158:161], v135 offset:2048
	ds_read_b128 v[162:165], v135 offset:3072
	ds_read_b128 v[166:169], v143
	ds_read_b128 v[170:173], v143 offset:1024
	ds_read_b128 v[174:177], v143 offset:2048
	ds_read_b128 v[178:181], v143 offset:3072
	s_cmp_eq_u32 s69, 28
	s_cselect_b32 s54, s64, s67
	s_cselect_b32 s55, s45, s68
	s_cselect_b32 s52, s46, s65
	s_cselect_b32 s53, s47, s66
	s_add_u32 s10, s54, 0x80
	s_addc_u32 s11, s55, 0
	s_add_u32 s56, s67, s22
	s_addc_u32 s57, s68, s23
	s_add_u32 s56, s56, 0xffffff80
	s_addc_u32 s57, s57, -1
	s_add_i32 m0, s6, 0xc000
	ds_read_b128 v[182:185], v145
	ds_read_b128 v[186:189], v145 offset:1024
	ds_read_b128 v[190:193], v145 offset:2048
	ds_read_b128 v[194:197], v145 offset:3072
	ds_read_b128 v[198:201], v145 offset:4096
	ds_read_b128 v[202:205], v145 offset:5120
	ds_read_b128 v[206:209], v145 offset:6144
	ds_read_b128 v[210:213], v145 offset:7168
	s_nop 0
	global_load_lds_dwordx4 v134, s[56:57]
	s_add_i32 m0, s6, 0xe000
	s_nop 0
	global_load_lds_dwordx4 v130, s[56:57]
	s_waitcnt vmcnt(8)
	s_waitcnt lgkmcnt(0)
	s_barrier
	s_setprio 1
	s_waitcnt lgkmcnt(0)
	v_mfma_f32_16x16x32_bf16 v[124:127], v[150:153], v[182:185], v[124:127]
	v_mfma_f32_16x16x32_bf16 v[120:123], v[158:161], v[182:185], v[120:123]
	v_mfma_f32_16x16x32_bf16 v[104:107], v[158:161], v[190:193], v[104:107]
	v_mfma_f32_16x16x32_bf16 v[108:111], v[150:153], v[190:193], v[108:111]
	v_mfma_f32_16x16x32_bf16 v[92:95], v[150:153], v[198:201], v[92:95]
	v_mfma_f32_16x16x32_bf16 v[88:91], v[158:161], v[198:201], v[88:91]
	v_mfma_f32_16x16x32_bf16 v[72:75], v[158:161], v[206:209], v[72:75]
	v_mfma_f32_16x16x32_bf16 v[76:79], v[150:153], v[206:209], v[76:79]
	v_mfma_f32_16x16x32_bf16 v[68:71], v[166:169], v[206:209], v[68:71]
	v_mfma_f32_16x16x32_bf16 v[64:67], v[174:177], v[206:209], v[64:67]
	v_mfma_f32_16x16x32_bf16 v[80:83], v[174:177], v[198:201], v[80:83]
	v_mfma_f32_16x16x32_bf16 v[84:87], v[166:169], v[198:201], v[84:87]
	v_mfma_f32_16x16x32_bf16 v[100:103], v[166:169], v[190:193], v[100:103]
	v_mfma_f32_16x16x32_bf16 v[96:99], v[174:177], v[190:193], v[96:99]
	v_mfma_f32_16x16x32_bf16 v[112:115], v[174:177], v[182:185], v[112:115]
	v_mfma_f32_16x16x32_bf16 v[116:119], v[166:169], v[182:185], v[116:119]
	v_mfma_f32_16x16x32_bf16 v[124:127], v[154:157], v[186:189], v[124:127]
	v_mfma_f32_16x16x32_bf16 v[120:123], v[162:165], v[186:189], v[120:123]
	v_mfma_f32_16x16x32_bf16 v[104:107], v[162:165], v[194:197], v[104:107]
	v_mfma_f32_16x16x32_bf16 v[108:111], v[154:157], v[194:197], v[108:111]
	v_mfma_f32_16x16x32_bf16 v[92:95], v[154:157], v[202:205], v[92:95]
	v_mfma_f32_16x16x32_bf16 v[88:91], v[162:165], v[202:205], v[88:91]
	v_mfma_f32_16x16x32_bf16 v[72:75], v[162:165], v[210:213], v[72:75]
	v_mfma_f32_16x16x32_bf16 v[76:79], v[154:157], v[210:213], v[76:79]
	v_mfma_f32_16x16x32_bf16 v[68:71], v[170:173], v[210:213], v[68:71]
	v_mfma_f32_16x16x32_bf16 v[64:67], v[178:181], v[210:213], v[64:67]
	v_mfma_f32_16x16x32_bf16 v[80:83], v[178:181], v[202:205], v[80:83]
	v_mfma_f32_16x16x32_bf16 v[84:87], v[170:173], v[202:205], v[84:87]
	v_mfma_f32_16x16x32_bf16 v[100:103], v[170:173], v[194:197], v[100:103]
	v_mfma_f32_16x16x32_bf16 v[96:99], v[178:181], v[194:197], v[96:99]
	v_mfma_f32_16x16x32_bf16 v[112:115], v[178:181], v[186:189], v[112:115]
	v_mfma_f32_16x16x32_bf16 v[116:119], v[170:173], v[186:189], v[116:119]
	s_setprio 0
	s_barrier
	s_add_i32 s70, s59, s3
	s_mov_b64 s[56:57], s[52:53]
	s_mov_b32 m0, s70
	ds_read_b128 v[182:185], v145 offset:16384
	ds_read_b128 v[186:189], v145 offset:17408
	ds_read_b128 v[190:193], v145 offset:18432
	ds_read_b128 v[194:197], v145 offset:19456
	ds_read_b128 v[198:201], v145 offset:20480
	ds_read_b128 v[202:205], v145 offset:21504
	ds_read_b128 v[206:209], v145 offset:22528
	ds_read_b128 v[210:213], v145 offset:23552
	s_nop 0
	global_load_lds_dwordx4 v149, s[56:57]
	s_add_i32 m0, s70, 0x2000
	s_nop 0
	global_load_lds_dwordx4 v128, s[56:57]
	s_add_u32 s56, s52, s16
	s_addc_u32 s57, s53, s17
	s_add_i32 s72, s60, s3
	s_mov_b64 s[70:71], s[56:57]
	s_mov_b32 m0, s72
	s_nop 0
	global_load_lds_dwordx4 v149, s[70:71]
	s_add_i32 m0, s72, 0x2000
	s_nop 0
	global_load_lds_dwordx4 v128, s[70:71]
	s_mov_b64 s[70:71], s[54:55]
	s_mov_b32 m0, s6
	s_nop 0
	global_load_lds_dwordx4 v134, s[70:71]
	s_mov_b32 m0, s7
	s_nop 0
	global_load_lds_dwordx4 v130, s[70:71]
	s_waitcnt vmcnt(8)
	s_waitcnt lgkmcnt(0)
	s_barrier
	s_setprio 1
	s_waitcnt lgkmcnt(0)
	v_mfma_f32_16x16x32_bf16 v[60:63], v[150:153], v[182:185], v[60:63]
	v_mfma_f32_16x16x32_bf16 v[56:59], v[158:161], v[182:185], v[56:59]
	v_mfma_f32_16x16x32_bf16 v[40:43], v[158:161], v[190:193], v[40:43]
	v_mfma_f32_16x16x32_bf16 v[44:47], v[150:153], v[190:193], v[44:47]
	v_mfma_f32_16x16x32_bf16 v[28:31], v[150:153], v[198:201], v[28:31]
	v_mfma_f32_16x16x32_bf16 v[24:27], v[158:161], v[198:201], v[24:27]
	v_mfma_f32_16x16x32_bf16 v[8:11], v[158:161], v[206:209], v[8:11]
	v_mfma_f32_16x16x32_bf16 v[12:15], v[150:153], v[206:209], v[12:15]
	v_mfma_f32_16x16x32_bf16 v[4:7], v[166:169], v[206:209], v[4:7]
	v_mfma_f32_16x16x32_bf16 v[0:3], v[174:177], v[206:209], v[0:3]
	v_mfma_f32_16x16x32_bf16 v[16:19], v[174:177], v[198:201], v[16:19]
	v_mfma_f32_16x16x32_bf16 v[20:23], v[166:169], v[198:201], v[20:23]
	v_mfma_f32_16x16x32_bf16 v[36:39], v[166:169], v[190:193], v[36:39]
	v_mfma_f32_16x16x32_bf16 v[32:35], v[174:177], v[190:193], v[32:35]
	v_mfma_f32_16x16x32_bf16 v[48:51], v[174:177], v[182:185], v[48:51]
	v_mfma_f32_16x16x32_bf16 v[52:55], v[166:169], v[182:185], v[52:55]
	v_mfma_f32_16x16x32_bf16 v[60:63], v[154:157], v[186:189], v[60:63]
	v_mfma_f32_16x16x32_bf16 v[56:59], v[162:165], v[186:189], v[56:59]
	v_mfma_f32_16x16x32_bf16 v[40:43], v[162:165], v[194:197], v[40:43]
	v_mfma_f32_16x16x32_bf16 v[44:47], v[154:157], v[194:197], v[44:47]
	v_mfma_f32_16x16x32_bf16 v[28:31], v[154:157], v[202:205], v[28:31]
	v_mfma_f32_16x16x32_bf16 v[24:27], v[162:165], v[202:205], v[24:27]
	v_mfma_f32_16x16x32_bf16 v[8:11], v[162:165], v[210:213], v[8:11]
	v_mfma_f32_16x16x32_bf16 v[12:15], v[154:157], v[210:213], v[12:15]
	v_mfma_f32_16x16x32_bf16 v[4:7], v[170:173], v[210:213], v[4:7]
	v_mfma_f32_16x16x32_bf16 v[0:3], v[178:181], v[210:213], v[0:3]
	v_mfma_f32_16x16x32_bf16 v[16:19], v[178:181], v[202:205], v[16:19]
	v_mfma_f32_16x16x32_bf16 v[20:23], v[170:173], v[202:205], v[20:23]
	v_mfma_f32_16x16x32_bf16 v[36:39], v[170:173], v[194:197], v[36:39]
	v_mfma_f32_16x16x32_bf16 v[32:35], v[178:181], v[194:197], v[32:35]
	v_mfma_f32_16x16x32_bf16 v[48:51], v[178:181], v[186:189], v[48:51]
	v_mfma_f32_16x16x32_bf16 v[52:55], v[170:173], v[186:189], v[52:55]
	s_setprio 0
	s_barrier
; #define PG8_STAGE(bufoff, gbase, voff) do { const char* _gb = (const char*)(gbase); asm volatile("" : "+s"(_gb));     \
;         _Pragma("unroll") for (int _i = 0; _i < 2; ++_i) \
;         __builtin_amdgcn_global_load_lds((const unsigned*)(_gb + (voff)[_i]), (LAS unsigned*)(lds + (bufoff) + ldsw + _i * 8192), 16, 0, 0); } while (0)
; #define PG8_VOFF_OPAQUE asm volatile("" : "+v"(voffA[0]), "+v"(voffA[1]), "+v"(voffB[0]), "+v"(voffB[1]))
; #define PG8_LDA(dst, b, h) do { _Pragma("unroll") for (int m = 0; m < 4; ++m) _Pragma("unroll") for (int k = 0; k < 2; ++k) dst[m][k] = *(const LAS bf16x8*)(lds + PG8_SA(b, h) + aoff + m * 2048 + k * 1024); } while (0)
; #define PG8_LDB(dst, b, h) do { _Pragma("unroll") for (int n = 0; n < 2; ++n) _Pragma("unroll") for (int k = 0; k < 2; ++k) dst[n][k] = *(const LAS bf16x8*)(lds + PG8_SB(b, h) + boff + n * 2048 + k * 1024); } while (0)
; template <class Epi>
; __device__ __forceinline__ void gemm_phase(LAS unsigned char* lds, const Gemm g, const StaticOrder& S, const Epi& E) {
;     ...
;         for (int t = 0; t < nt; t += 2) {
;             PG8_VOFF_OPAQUE;
;             const bool last = (t == nt - 2);
;             const char* a1 = cA + (size_t)(t + 1) * kstepA;
;             const char* a2 = last ? nA : cA + (size_t)(t + 2) * kstepA; const char* b2 = last ? nB : cB + (size_t)(t + 2) * kstepB;
;             const char* a3 = a2 + kstepA; const char* b3 = b2 + kstepB;
;             PG8_LDB(B0, 0, 0); PG8_LDB(B1, 0, 1); PG8_SCHED; PG8_LDA(At, 0, 0); PG8_STAGE(PG8_SA(1, 1), a1 + hstepA, voffA);
;             PG8_WAIT_V(8); PG8_WAIT_L(0); PG8_BAR; PG8_MMA2(0, At, B0, B1); PG8_BAR; PG8_SCHED;
;             PG8_LDA(At, 0, 1); PG8_STAGE(PG8_SB(0, 0), b2, voffB); PG8_STAGE(PG8_SB(0, 1), b2 + hstepB, voffB); PG8_STAGE(PG8_SA(0, 0), a2, voffA);
;             PG8_WAIT_V(8); PG8_WAIT_L(0); PG8_BAR; PG8_MMA2(1, At, B0, B1); PG8_BAR; PG8_SCHED;
;             PG8_LDB(B0, 1, 0); PG8_LDB(B1, 1, 1); PG8_SCHED; PG8_LDA(At, 1, 0); PG8_STAGE(PG8_SA(0, 1), a2 + hstepA, voffA);
;             PG8_WAIT_V(8); PG8_WAIT_L(0); PG8_BAR; PG8_MMA2(0, At, B0, B1); PG8_BAR; PG8_SCHED;
;             PG8_LDA(At, 1, 1); PG8_STAGE(PG8_SB(1, 0), b3, voffB); PG8_STAGE(PG8_SB(1, 1), b3 + hstepB, voffB); PG8_STAGE(PG8_SA(1, 0), a3, voffA);
;             PG8_WAIT_V(8); PG8_WAIT_L(0); PG8_BAR; PG8_MMA2(1, At, B0, B1); PG8_BAR; PG8_SCHED;
;         }
	s_add_i32 s70, 0, 0x18000
	v_add_u32_e32 v132, s70, v131
	s_add_i32 s71, 0, 0x1c000
	ds_read_b128 v[150:153], v132
	ds_read_b128 v[154:157], v132 offset:1024
	ds_read_b128 v[158:161], v132 offset:2048
	ds_read_b128 v[162:165], v132 offset:3072
	v_add_u32_e32 v132, s71, v131
	ds_read_b128 v[166:169], v132
	ds_read_b128 v[170:173], v132 offset:1024
	ds_read_b128 v[174:177], v132 offset:2048
	ds_read_b128 v[178:181], v132 offset:3072
	s_add_u32 s54, s54, s22
	s_addc_u32 s55, s55, s23
	s_mov_b32 m0, s18
	ds_read_b128 v[182:185], v145 offset:32768
	ds_read_b128 v[186:189], v145 offset:33792
	ds_read_b128 v[190:193], v145 offset:34816
	ds_read_b128 v[194:197], v145 offset:35840
	ds_read_b128 v[198:201], v145 offset:36864
	ds_read_b128 v[202:205], v145 offset:37888
	ds_read_b128 v[206:209], v145 offset:38912
	ds_read_b128 v[210:213], v145 offset:39936
	s_nop 0
	global_load_lds_dwordx4 v134, s[54:55]
	s_mov_b32 m0, s19
	s_nop 0
	global_load_lds_dwordx4 v130, s[54:55]
	s_waitcnt vmcnt(8)
	s_waitcnt lgkmcnt(0)
	s_barrier
	s_setprio 1
	s_waitcnt lgkmcnt(0)
	v_mfma_f32_16x16x32_bf16 v[124:127], v[150:153], v[182:185], v[124:127]
	v_mfma_f32_16x16x32_bf16 v[120:123], v[158:161], v[182:185], v[120:123]
	v_mfma_f32_16x16x32_bf16 v[104:107], v[158:161], v[190:193], v[104:107]
	v_mfma_f32_16x16x32_bf16 v[108:111], v[150:153], v[190:193], v[108:111]
	v_mfma_f32_16x16x32_bf16 v[92:95], v[150:153], v[198:201], v[92:95]
	v_mfma_f32_16x16x32_bf16 v[88:91], v[158:161], v[198:201], v[88:91]
	v_mfma_f32_16x16x32_bf16 v[72:75], v[158:161], v[206:209], v[72:75]
	v_mfma_f32_16x16x32_bf16 v[76:79], v[150:153], v[206:209], v[76:79]
	v_mfma_f32_16x16x32_bf16 v[68:71], v[166:169], v[206:209], v[68:71]
	v_mfma_f32_16x16x32_bf16 v[64:67], v[174:177], v[206:209], v[64:67]
	v_mfma_f32_16x16x32_bf16 v[80:83], v[174:177], v[198:201], v[80:83]
	v_mfma_f32_16x16x32_bf16 v[84:87], v[166:169], v[198:201], v[84:87]
	v_mfma_f32_16x16x32_bf16 v[100:103], v[166:169], v[190:193], v[100:103]
	v_mfma_f32_16x16x32_bf16 v[96:99], v[174:177], v[190:193], v[96:99]
	v_mfma_f32_16x16x32_bf16 v[112:115], v[174:177], v[182:185], v[112:115]
	v_mfma_f32_16x16x32_bf16 v[116:119], v[166:169], v[182:185], v[116:119]
	v_mfma_f32_16x16x32_bf16 v[124:127], v[154:157], v[186:189], v[124:127]
	v_mfma_f32_16x16x32_bf16 v[120:123], v[162:165], v[186:189], v[120:123]
	v_mfma_f32_16x16x32_bf16 v[104:107], v[162:165], v[194:197], v[104:107]
	v_mfma_f32_16x16x32_bf16 v[108:111], v[154:157], v[194:197], v[108:111]
	v_mfma_f32_16x16x32_bf16 v[92:95], v[154:157], v[202:205], v[92:95]
	v_mfma_f32_16x16x32_bf16 v[88:91], v[162:165], v[202:205], v[88:91]
	v_mfma_f32_16x16x32_bf16 v[72:75], v[162:165], v[210:213], v[72:75]
	v_mfma_f32_16x16x32_bf16 v[76:79], v[154:157], v[210:213], v[76:79]
	v_mfma_f32_16x16x32_bf16 v[68:71], v[170:173], v[210:213], v[68:71]
	v_mfma_f32_16x16x32_bf16 v[64:67], v[178:181], v[210:213], v[64:67]
	v_mfma_f32_16x16x32_bf16 v[80:83], v[178:181], v[202:205], v[80:83]
	v_mfma_f32_16x16x32_bf16 v[84:87], v[170:173], v[202:205], v[84:87]
	v_mfma_f32_16x16x32_bf16 v[100:103], v[170:173], v[194:197], v[100:103]
	v_mfma_f32_16x16x32_bf16 v[96:99], v[178:181], v[194:197], v[96:99]
	v_mfma_f32_16x16x32_bf16 v[112:115], v[178:181], v[186:189], v[112:115]
	v_mfma_f32_16x16x32_bf16 v[116:119], v[170:173], v[186:189], v[116:119]
	s_setprio 0
	s_barrier
	s_add_u32 s52, s52, 0x80
	s_addc_u32 s53, s53, 0
	s_add_i32 s54, s70, s3
	s_mov_b32 m0, s54
	ds_read_b128 v[182:185], v145 offset:49152
	ds_read_b128 v[186:189], v145 offset:50176
	ds_read_b128 v[190:193], v145 offset:51200
	ds_read_b128 v[194:197], v145 offset:52224
	ds_read_b128 v[198:201], v145 offset:53248
	ds_read_b128 v[202:205], v145 offset:54272
	ds_read_b128 v[206:209], v145 offset:55296
	ds_read_b128 v[210:213], v145 offset:56320
	s_nop 0
	global_load_lds_dwordx4 v149, s[52:53]
	s_add_i32 m0, s54, 0x2000
	s_nop 0
	global_load_lds_dwordx4 v128, s[52:53]
	s_add_u32 s52, s56, 0x80
	s_addc_u32 s53, s57, 0
	s_add_i32 s54, s71, s3
	s_mov_b32 m0, s54
	s_nop 0
	global_load_lds_dwordx4 v149, s[52:53]
	s_add_i32 m0, s54, 0x2000
	s_nop 0
	global_load_lds_dwordx4 v128, s[52:53]
	s_mov_b32 m0, s33
	s_nop 0
	global_load_lds_dwordx4 v134, s[10:11]
	s_mov_b32 m0, s43
	s_nop 0
	global_load_lds_dwordx4 v130, s[10:11]
	s_waitcnt vmcnt(8)
	s_waitcnt lgkmcnt(0)
	s_barrier
	s_setprio 1
	s_waitcnt lgkmcnt(0)
	v_mfma_f32_16x16x32_bf16 v[60:63], v[150:153], v[182:185], v[60:63]
	v_mfma_f32_16x16x32_bf16 v[56:59], v[158:161], v[182:185], v[56:59]
	v_mfma_f32_16x16x32_bf16 v[40:43], v[158:161], v[190:193], v[40:43]
	v_mfma_f32_16x16x32_bf16 v[44:47], v[150:153], v[190:193], v[44:47]
	v_mfma_f32_16x16x32_bf16 v[28:31], v[150:153], v[198:201], v[28:31]
	v_mfma_f32_16x16x32_bf16 v[24:27], v[158:161], v[198:201], v[24:27]
	v_mfma_f32_16x16x32_bf16 v[8:11], v[158:161], v[206:209], v[8:11]
	v_mfma_f32_16x16x32_bf16 v[12:15], v[150:153], v[206:209], v[12:15]
	v_mfma_f32_16x16x32_bf16 v[4:7], v[166:169], v[206:209], v[4:7]
	v_mfma_f32_16x16x32_bf16 v[0:3], v[174:177], v[206:209], v[0:3]
	v_mfma_f32_16x16x32_bf16 v[16:19], v[174:177], v[198:201], v[16:19]
	v_mfma_f32_16x16x32_bf16 v[20:23], v[166:169], v[198:201], v[20:23]
	v_mfma_f32_16x16x32_bf16 v[36:39], v[166:169], v[190:193], v[36:39]
	v_mfma_f32_16x16x32_bf16 v[32:35], v[174:177], v[190:193], v[32:35]
	v_mfma_f32_16x16x32_bf16 v[48:51], v[174:177], v[182:185], v[48:51]
	v_mfma_f32_16x16x32_bf16 v[52:55], v[166:169], v[182:185], v[52:55]
	v_mfma_f32_16x16x32_bf16 v[60:63], v[154:157], v[186:189], v[60:63]
	v_mfma_f32_16x16x32_bf16 v[56:59], v[162:165], v[186:189], v[56:59]
	v_mfma_f32_16x16x32_bf16 v[40:43], v[162:165], v[194:197], v[40:43]
	v_mfma_f32_16x16x32_bf16 v[44:47], v[154:157], v[194:197], v[44:47]
	v_mfma_f32_16x16x32_bf16 v[28:31], v[154:157], v[202:205], v[28:31]
	v_mfma_f32_16x16x32_bf16 v[24:27], v[162:165], v[202:205], v[24:27]
	v_mfma_f32_16x16x32_bf16 v[8:11], v[162:165], v[210:213], v[8:11]
	v_mfma_f32_16x16x32_bf16 v[12:15], v[154:157], v[210:213], v[12:15]
	v_mfma_f32_16x16x32_bf16 v[4:7], v[170:173], v[210:213], v[4:7]
	v_mfma_f32_16x16x32_bf16 v[0:3], v[178:181], v[210:213], v[0:3]
	v_mfma_f32_16x16x32_bf16 v[16:19], v[178:181], v[202:205], v[16:19]
	v_mfma_f32_16x16x32_bf16 v[20:23], v[170:173], v[202:205], v[20:23]
	v_mfma_f32_16x16x32_bf16 v[36:39], v[170:173], v[194:197], v[36:39]
	v_mfma_f32_16x16x32_bf16 v[32:35], v[178:181], v[194:197], v[32:35]
	v_mfma_f32_16x16x32_bf16 v[48:51], v[178:181], v[186:189], v[48:51]
	v_mfma_f32_16x16x32_bf16 v[52:55], v[170:173], v[186:189], v[52:55]
	s_setprio 0
	s_barrier
	s_add_i32 s69, s69, 2
	s_add_u32 s65, s65, 0x100
	s_addc_u32 s66, s66, 0
	s_add_u32 s67, s67, 0x100
	s_addc_u32 s68, s68, 0
	s_cmp_gt_u32 s69, 29
	s_cbranch_scc0 .LBB0_1207
	s_and_b64 vcc, exec, s[40:41]
	s_cbranch_vccz .LBB0_1210
	s_barrier

; #define PG8_STAGE(bufoff, gbase, voff) do { const char* _gb = (const char*)(gbase); asm volatile("" : "+s"(_gb));     \
;         _Pragma("unroll") for (int _i = 0; _i < 2; ++_i) \
;         __builtin_amdgcn_global_load_lds((const unsigned*)(_gb + (voff)[_i]), (LAS unsigned*)(lds + (bufoff) + ldsw + _i * 8192), 16, 0, 0); } while (0)
; #define PG8_VOFF_OPAQUE asm volatile("" : "+v"(voffA[0]), "+v"(voffA[1]), "+v"(voffB[0]), "+v"(voffB[1]))
; #define PG8_LDA(dst, b, h) do { _Pragma("unroll") for (int m = 0; m < 4; ++m) _Pragma("unroll") for (int k = 0; k < 2; ++k) dst[m][k] = *(const LAS bf16x8*)(lds + PG8_SA(b, h) + aoff + m * 2048 + k * 1024); } while (0)
; #define PG8_LDB(dst, b, h) do { _Pragma("unroll") for (int n = 0; n < 2; ++n) _Pragma("unroll") for (int k = 0; k < 2; ++k) dst[n][k] = *(const LAS bf16x8*)(lds + PG8_SB(b, h) + boff + n * 2048 + k * 1024); } while (0)
; #define PG8_WAIT_V(n) asm volatile("s_waitcnt vmcnt(" #n ")" ::: "memory")
; #define PG8_WAIT_L(n) asm volatile("s_waitcnt lgkmcnt(" #n ")" ::: "memory")
; template <class Epi>
; __device__ __forceinline__ void gemm_phase(LAS unsigned char* lds, const Gemm g, const StaticOrder& S, const Epi& E) {
;     ...
;         const bool has_next = S.next(ui + 1, nxt);
;         const char* nA = has_next ? (const char*)gA + (size_t)nxt.pm * tstepA + (size_t)nxt.pn * acolb + (size_t)nxt.kofs * kstepA : cA; const char* nB = has_next ? (const char*)gB + (size_t)nxt.pn * tstepB + (size_t)nxt.kofs * kstepB : cB;
;         const int nt = cur.nt;
;         for (int t = 0; t < nt; t += 2) {
;             PG8_VOFF_OPAQUE;
;             const bool last = (t == nt - 2);
;             const char* a1 = cA + (size_t)(t + 1) * kstepA;
;             const char* a2 = last ? nA : cA + (size_t)(t + 2) * kstepA; const char* b2 = last ? nB : cB + (size_t)(t + 2) * kstepB;
;             const char* a3 = a2 + kstepA; const char* b3 = b2 + kstepB;
;             PG8_LDB(B0, 0, 0); PG8_LDB(B1, 0, 1); PG8_SCHED; PG8_LDA(At, 0, 0); PG8_STAGE(PG8_SA(1, 1), a1 + hstepA, voffA);
;             PG8_WAIT_V(8); PG8_WAIT_L(0); PG8_BAR; PG8_MMA2(0, At, B0, B1); PG8_BAR; PG8_SCHED;
;             PG8_LDA(At, 0, 1); PG8_STAGE(PG8_SB(0, 0), b2, voffB); PG8_STAGE(PG8_SB(0, 1), b2 + hstepB, voffB); PG8_STAGE(PG8_SA(0, 0), a2, voffA);
;             PG8_WAIT_V(8); PG8_WAIT_L(0); PG8_BAR; PG8_MMA2(1, At, B0, B1); PG8_BAR; PG8_SCHED;
.LBB0_1287:
	s_waitcnt lgkmcnt(0)
	ds_read_b128 v[128:131], v179
	ds_read_b128 v[132:135], v179 offset:1024
	ds_read_b128 v[136:139], v179 offset:2048
	ds_read_b128 v[140:143], v179 offset:3072
	ds_read_b128 v[144:147], v181
	ds_read_b128 v[148:151], v181 offset:1024
	ds_read_b128 v[152:155], v181 offset:2048
	ds_read_b128 v[156:159], v181 offset:3072
	s_add_i32 s89, s48, 2
	s_cmp_eq_u32 s84, s48
	s_cselect_b32 s52, s14, s87
	s_cselect_b32 s53, s15, s88
	s_cselect_b32 s50, s46, s85
	s_cselect_b32 s51, s47, s86
	s_add_u32 s48, s52, 0x8000
	s_addc_u32 s49, s53, 0
	s_add_u32 s54, s87, s34
	s_addc_u32 s55, s88, s35
	s_add_u32 s54, s54, 0xffff8000
	s_addc_u32 s55, s55, -1
	s_add_i32 m0, s6, 0xc000
	ds_read_b128 v[160:163], v183
	ds_read_b128 v[164:167], v183 offset:1024
	ds_read_b128 v[168:171], v183 offset:2048
	ds_read_b128 v[172:175], v183 offset:3072
	ds_read_b128 v[188:191], v183 offset:4096
	ds_read_b128 v[192:195], v183 offset:5120
	ds_read_b128 v[196:199], v183 offset:6144
	ds_read_b128 v[200:203], v183 offset:7168
	s_nop 0
	global_load_lds_dwordx4 v176, s[54:55]
	s_add_i32 m0, s6, 0xe000
	s_nop 0
	global_load_lds_dwordx4 v180, s[54:55]
	s_waitcnt vmcnt(8)
	s_waitcnt lgkmcnt(0)
	s_barrier
	s_setprio 1
	s_waitcnt lgkmcnt(0)
	v_mfma_f32_16x16x32_bf16 v[124:127], v[128:131], v[160:163], v[124:127]
	v_mfma_f32_16x16x32_bf16 v[120:123], v[136:139], v[160:163], v[120:123]
	v_mfma_f32_16x16x32_bf16 v[112:115], v[136:139], v[168:171], v[112:115]
	v_mfma_f32_16x16x32_bf16 v[116:119], v[128:131], v[168:171], v[116:119]
	v_mfma_f32_16x16x32_bf16 v[108:111], v[128:131], v[188:191], v[108:111]
	v_mfma_f32_16x16x32_bf16 v[104:107], v[136:139], v[188:191], v[104:107]
	v_mfma_f32_16x16x32_bf16 v[96:99], v[136:139], v[196:199], v[96:99]
	v_mfma_f32_16x16x32_bf16 v[100:103], v[128:131], v[196:199], v[100:103]
	v_mfma_f32_16x16x32_bf16 v[68:71], v[144:147], v[196:199], v[68:71]
	v_mfma_f32_16x16x32_bf16 v[64:67], v[152:155], v[196:199], v[64:67]
	v_mfma_f32_16x16x32_bf16 v[72:75], v[152:155], v[188:191], v[72:75]
	v_mfma_f32_16x16x32_bf16 v[76:79], v[144:147], v[188:191], v[76:79]
	v_mfma_f32_16x16x32_bf16 v[84:87], v[144:147], v[168:171], v[84:87]
	v_mfma_f32_16x16x32_bf16 v[80:83], v[152:155], v[168:171], v[80:83]
	v_mfma_f32_16x16x32_bf16 v[88:91], v[152:155], v[160:163], v[88:91]
	v_mfma_f32_16x16x32_bf16 v[92:95], v[144:147], v[160:163], v[92:95]
	v_mfma_f32_16x16x32_bf16 v[124:127], v[132:135], v[164:167], v[124:127]
	v_mfma_f32_16x16x32_bf16 v[120:123], v[140:143], v[164:167], v[120:123]
	v_mfma_f32_16x16x32_bf16 v[112:115], v[140:143], v[172:175], v[112:115]
	v_mfma_f32_16x16x32_bf16 v[116:119], v[132:135], v[172:175], v[116:119]
	v_mfma_f32_16x16x32_bf16 v[108:111], v[132:135], v[192:195], v[108:111]
	v_mfma_f32_16x16x32_bf16 v[104:107], v[140:143], v[192:195], v[104:107]
	v_mfma_f32_16x16x32_bf16 v[96:99], v[140:143], v[200:203], v[96:99]
	v_mfma_f32_16x16x32_bf16 v[100:103], v[132:135], v[200:203], v[100:103]
	v_mfma_f32_16x16x32_bf16 v[68:71], v[148:151], v[200:203], v[68:71]
	v_mfma_f32_16x16x32_bf16 v[64:67], v[156:159], v[200:203], v[64:67]
	v_mfma_f32_16x16x32_bf16 v[72:75], v[156:159], v[192:195], v[72:75]
	v_mfma_f32_16x16x32_bf16 v[76:79], v[148:151], v[192:195], v[76:79]
	v_mfma_f32_16x16x32_bf16 v[84:87], v[148:151], v[172:175], v[84:87]
	v_mfma_f32_16x16x32_bf16 v[80:83], v[156:159], v[172:175], v[80:83]
	v_mfma_f32_16x16x32_bf16 v[88:91], v[156:159], v[164:167], v[88:91]
	v_mfma_f32_16x16x32_bf16 v[92:95], v[148:151], v[164:167], v[92:95]
	s_setprio 0
	s_barrier
	s_add_i32 s90, s72, s3
	s_mov_b64 s[54:55], s[50:51]
	s_mov_b32 m0, s90
	ds_read_b128 v[160:163], v183 offset:16384
	ds_read_b128 v[164:167], v183 offset:17408
	ds_read_b128 v[168:171], v183 offset:18432
	ds_read_b128 v[172:175], v183 offset:19456
	ds_read_b128 v[188:191], v183 offset:20480
	ds_read_b128 v[192:195], v183 offset:21504
	ds_read_b128 v[196:199], v183 offset:22528
	ds_read_b128 v[200:203], v183 offset:23552
	s_nop 0
	global_load_lds_dwordx4 v178, s[54:55]
	s_add_i32 m0, s90, 0x2000
	s_nop 0
	global_load_lds_dwordx4 v182, s[54:55]
	s_add_u32 s54, s50, s20
	s_addc_u32 s55, s51, s21
	s_add_i32 s92, s73, s3
	s_mov_b64 s[90:91], s[54:55]
	s_mov_b32 m0, s92
	s_nop 0
	global_load_lds_dwordx4 v178, s[90:91]
	s_add_i32 m0, s92, 0x2000
	s_nop 0
	global_load_lds_dwordx4 v182, s[90:91]
	s_mov_b64 s[90:91], s[52:53]
	s_mov_b32 m0, s6
	s_nop 0
	global_load_lds_dwordx4 v176, s[90:91]
	s_mov_b32 m0, s7
	s_nop 0
	global_load_lds_dwordx4 v180, s[90:91]
	s_waitcnt vmcnt(8)
	s_waitcnt lgkmcnt(0)
	s_barrier
; #define PG8_STAGE(bufoff, gbase, voff) do { const char* _gb = (const char*)(gbase); asm volatile("" : "+s"(_gb));     \
;         _Pragma("unroll") for (int _i = 0; _i < 2; ++_i) \
;         __builtin_amdgcn_global_load_lds((const unsigned*)(_gb + (voff)[_i]), (LAS unsigned*)(lds + (bufoff) + ldsw + _i * 8192), 16, 0, 0); } while (0)
; #define PG8_LDA(dst, b, h) do { _Pragma("unroll") for (int m = 0; m < 4; ++m) _Pragma("unroll") for (int k = 0; k < 2; ++k) dst[m][k] = *(const LAS bf16x8*)(lds + PG8_SA(b, h) + aoff + m * 2048 + k * 1024); } while (0)
; #define PG8_LDB(dst, b, h) do { _Pragma("unroll") for (int n = 0; n < 2; ++n) _Pragma("unroll") for (int k = 0; k < 2; ++k) dst[n][k] = *(const LAS bf16x8*)(lds + PG8_SB(b, h) + boff + n * 2048 + k * 1024); } while (0)
; #define PG8_WAIT_V(n) asm volatile("s_waitcnt vmcnt(" #n ")" ::: "memory")
; #define PG8_WAIT_L(n) asm volatile("s_waitcnt lgkmcnt(" #n ")" ::: "memory")
; #define PG8_BAR __builtin_amdgcn_s_barrier()
; #define PG8_SCHED __builtin_amdgcn_sched_barrier(0)
; template <class Epi>
; __device__ __forceinline__ void gemm_phase(LAS unsigned char* lds, const Gemm g, const StaticOrder& S, const Epi& E) {
;     ...
;             PG8_WAIT_V(8); PG8_WAIT_L(0); PG8_BAR; PG8_MMA2(1, At, B0, B1); PG8_BAR; PG8_SCHED;
;             PG8_LDB(B0, 1, 0); PG8_LDB(B1, 1, 1); PG8_SCHED; PG8_LDA(At, 1, 0); PG8_STAGE(PG8_SA(0, 1), a2 + hstepA, voffA);
;             PG8_WAIT_V(8); PG8_WAIT_L(0); PG8_BAR; PG8_MMA2(0, At, B0, B1); PG8_BAR; PG8_SCHED;
	s_setprio 1
	s_waitcnt lgkmcnt(0)
	v_mfma_f32_16x16x32_bf16 v[60:63], v[128:131], v[160:163], v[60:63]
	v_mfma_f32_16x16x32_bf16 v[56:59], v[136:139], v[160:163], v[56:59]
	v_mfma_f32_16x16x32_bf16 v[48:51], v[136:139], v[168:171], v[48:51]
	v_mfma_f32_16x16x32_bf16 v[52:55], v[128:131], v[168:171], v[52:55]
	v_mfma_f32_16x16x32_bf16 v[44:47], v[128:131], v[188:191], v[44:47]
	v_mfma_f32_16x16x32_bf16 v[40:43], v[136:139], v[188:191], v[40:43]
	v_mfma_f32_16x16x32_bf16 v[32:35], v[136:139], v[196:199], v[32:35]
	v_mfma_f32_16x16x32_bf16 v[36:39], v[128:131], v[196:199], v[36:39]
	v_mfma_f32_16x16x32_bf16 v[4:7], v[144:147], v[196:199], v[4:7]
	v_mfma_f32_16x16x32_bf16 v[0:3], v[152:155], v[196:199], v[0:3]
	v_mfma_f32_16x16x32_bf16 v[8:11], v[152:155], v[188:191], v[8:11]
	v_mfma_f32_16x16x32_bf16 v[12:15], v[144:147], v[188:191], v[12:15]
	v_mfma_f32_16x16x32_bf16 v[20:23], v[144:147], v[168:171], v[20:23]
	v_mfma_f32_16x16x32_bf16 v[16:19], v[152:155], v[168:171], v[16:19]
	v_mfma_f32_16x16x32_bf16 v[24:27], v[152:155], v[160:163], v[24:27]
	v_mfma_f32_16x16x32_bf16 v[28:31], v[144:147], v[160:163], v[28:31]
	v_mfma_f32_16x16x32_bf16 v[60:63], v[132:135], v[164:167], v[60:63]
	v_mfma_f32_16x16x32_bf16 v[56:59], v[140:143], v[164:167], v[56:59]
	v_mfma_f32_16x16x32_bf16 v[48:51], v[140:143], v[172:175], v[48:51]
	v_mfma_f32_16x16x32_bf16 v[52:55], v[132:135], v[172:175], v[52:55]
	v_mfma_f32_16x16x32_bf16 v[44:47], v[132:135], v[192:195], v[44:47]
	v_mfma_f32_16x16x32_bf16 v[40:43], v[140:143], v[192:195], v[40:43]
	v_mfma_f32_16x16x32_bf16 v[32:35], v[140:143], v[200:203], v[32:35]
	v_mfma_f32_16x16x32_bf16 v[36:39], v[132:135], v[200:203], v[36:39]
	v_mfma_f32_16x16x32_bf16 v[4:7], v[148:151], v[200:203], v[4:7]
	v_mfma_f32_16x16x32_bf16 v[0:3], v[156:159], v[200:203], v[0:3]
	v_mfma_f32_16x16x32_bf16 v[8:11], v[156:159], v[192:195], v[8:11]
	v_mfma_f32_16x16x32_bf16 v[12:15], v[148:151], v[192:195], v[12:15]
	v_mfma_f32_16x16x32_bf16 v[20:23], v[148:151], v[172:175], v[20:23]
	v_mfma_f32_16x16x32_bf16 v[16:19], v[156:159], v[172:175], v[16:19]
	v_mfma_f32_16x16x32_bf16 v[24:27], v[156:159], v[164:167], v[24:27]
	v_mfma_f32_16x16x32_bf16 v[28:31], v[148:151], v[164:167], v[28:31]
	s_setprio 0
	s_barrier
	s_add_i32 s90, 0, 0x18000
	s_add_i32 s91, 0, 0x1c000
	v_add_u32_e32 v140, s90, v207
	v_add_u32_e32 v156, s91, v207
	ds_read_b128 v[128:131], v140
	ds_read_b128 v[132:135], v140 offset:1024
	ds_read_b128 v[136:139], v140 offset:2048
	ds_read_b128 v[140:143], v140 offset:3072
	ds_read_b128 v[144:147], v156
	ds_read_b128 v[148:151], v156 offset:1024
	ds_read_b128 v[152:155], v156 offset:2048
	ds_read_b128 v[156:159], v156 offset:3072
	s_add_u32 s52, s52, s34
	s_addc_u32 s53, s53, s35
	s_mov_b32 m0, s18
	ds_read_b128 v[160:163], v183 offset:32768
	ds_read_b128 v[164:167], v183 offset:33792
	ds_read_b128 v[168:171], v183 offset:34816
	ds_read_b128 v[172:175], v183 offset:35840
	ds_read_b128 v[188:191], v183 offset:36864
	ds_read_b128 v[192:195], v183 offset:37888
	ds_read_b128 v[196:199], v183 offset:38912
	ds_read_b128 v[200:203], v183 offset:39936
	s_nop 0
	global_load_lds_dwordx4 v176, s[52:53]
	s_mov_b32 m0, s19
	s_nop 0
	global_load_lds_dwordx4 v180, s[52:53]
	s_waitcnt vmcnt(8)
	s_waitcnt lgkmcnt(0)
	s_barrier
	s_setprio 1
	s_waitcnt lgkmcnt(0)
	v_mfma_f32_16x16x32_bf16 v[124:127], v[128:131], v[160:163], v[124:127]
	v_mfma_f32_16x16x32_bf16 v[120:123], v[136:139], v[160:163], v[120:123]
	v_mfma_f32_16x16x32_bf16 v[112:115], v[136:139], v[168:171], v[112:115]
	v_mfma_f32_16x16x32_bf16 v[116:119], v[128:131], v[168:171], v[116:119]
	v_mfma_f32_16x16x32_bf16 v[108:111], v[128:131], v[188:191], v[108:111]
	v_mfma_f32_16x16x32_bf16 v[104:107], v[136:139], v[188:191], v[104:107]
	v_mfma_f32_16x16x32_bf16 v[96:99], v[136:139], v[196:199], v[96:99]
	v_mfma_f32_16x16x32_bf16 v[100:103], v[128:131], v[196:199], v[100:103]
	v_mfma_f32_16x16x32_bf16 v[68:71], v[144:147], v[196:199], v[68:71]
	v_mfma_f32_16x16x32_bf16 v[64:67], v[152:155], v[196:199], v[64:67]
	v_mfma_f32_16x16x32_bf16 v[72:75], v[152:155], v[188:191], v[72:75]
	v_mfma_f32_16x16x32_bf16 v[76:79], v[144:147], v[188:191], v[76:79]
	v_mfma_f32_16x16x32_bf16 v[84:87], v[144:147], v[168:171], v[84:87]
	v_mfma_f32_16x16x32_bf16 v[80:83], v[152:155], v[168:171], v[80:83]
	v_mfma_f32_16x16x32_bf16 v[88:91], v[152:155], v[160:163], v[88:91]
	v_mfma_f32_16x16x32_bf16 v[92:95], v[144:147], v[160:163], v[92:95]
	v_mfma_f32_16x16x32_bf16 v[124:127], v[132:135], v[164:167], v[124:127]
	v_mfma_f32_16x16x32_bf16 v[120:123], v[140:143], v[164:167], v[120:123]
	v_mfma_f32_16x16x32_bf16 v[112:115], v[140:143], v[172:175], v[112:115]
	v_mfma_f32_16x16x32_bf16 v[116:119], v[132:135], v[172:175], v[116:119]
	v_mfma_f32_16x16x32_bf16 v[108:111], v[132:135], v[192:195], v[108:111]
	v_mfma_f32_16x16x32_bf16 v[104:107], v[140:143], v[192:195], v[104:107]
	v_mfma_f32_16x16x32_bf16 v[96:99], v[140:143], v[200:203], v[96:99]
	v_mfma_f32_16x16x32_bf16 v[100:103], v[132:135], v[200:203], v[100:103]
	v_mfma_f32_16x16x32_bf16 v[68:71], v[148:151], v[200:203], v[68:71]
	v_mfma_f32_16x16x32_bf16 v[64:67], v[156:159], v[200:203], v[64:67]
	v_mfma_f32_16x16x32_bf16 v[72:75], v[156:159], v[192:195], v[72:75]
	v_mfma_f32_16x16x32_bf16 v[76:79], v[148:151], v[192:195], v[76:79]
	v_mfma_f32_16x16x32_bf16 v[84:87], v[148:151], v[172:175], v[84:87]
	v_mfma_f32_16x16x32_bf16 v[80:83], v[156:159], v[172:175], v[80:83]
	v_mfma_f32_16x16x32_bf16 v[88:91], v[156:159], v[164:167], v[88:91]
	v_mfma_f32_16x16x32_bf16 v[92:95], v[148:151], v[164:167], v[92:95]
	s_setprio 0
	s_barrier
; #define PG8_STAGE(bufoff, gbase, voff) do { const char* _gb = (const char*)(gbase); asm volatile("" : "+s"(_gb));     \
;         _Pragma("unroll") for (int _i = 0; _i < 2; ++_i) \
;         __builtin_amdgcn_global_load_lds((const unsigned*)(_gb + (voff)[_i]), (LAS unsigned*)(lds + (bufoff) + ldsw + _i * 8192), 16, 0, 0); } while (0)
; #define PG8_LDA(dst, b, h) do { _Pragma("unroll") for (int m = 0; m < 4; ++m) _Pragma("unroll") for (int k = 0; k < 2; ++k) dst[m][k] = *(const LAS bf16x8*)(lds + PG8_SA(b, h) + aoff + m * 2048 + k * 1024); } while (0)
; #define PG8_WAIT_V(n) asm volatile("s_waitcnt vmcnt(" #n ")" ::: "memory")
; #define PG8_WAIT_L(n) asm volatile("s_waitcnt lgkmcnt(" #n ")" ::: "memory")
; #define PG8_BAR __builtin_amdgcn_s_barrier()
; #define PG8_SCHED __builtin_amdgcn_sched_barrier(0)
; template <class Epi>
; __device__ __forceinline__ void gemm_phase(LAS unsigned char* lds, const Gemm g, const StaticOrder& S, const Epi& E) {
;     ...
;             PG8_LDA(At, 1, 1); PG8_STAGE(PG8_SB(1, 0), b3, voffB); PG8_STAGE(PG8_SB(1, 1), b3 + hstepB, voffB); PG8_STAGE(PG8_SA(1, 0), a3, voffA);
;             PG8_WAIT_V(8); PG8_WAIT_L(0); PG8_BAR; PG8_MMA2(1, At, B0, B1); PG8_BAR; PG8_SCHED;
;         }
;         if (wr == 0) PG8_BAR;
;         E(acc, cur, wr, wc, fr, fq);
;         if (!has_next) break;
	s_add_u32 s50, s50, 0x80
	s_addc_u32 s51, s51, 0
	s_add_i32 s52, s90, s3
	s_mov_b32 m0, s52
	ds_read_b128 v[160:163], v183 offset:49152
	ds_read_b128 v[164:167], v183 offset:50176
	ds_read_b128 v[168:171], v183 offset:51200
	ds_read_b128 v[172:175], v183 offset:52224
	ds_read_b128 v[188:191], v183 offset:53248
	ds_read_b128 v[192:195], v183 offset:54272
	ds_read_b128 v[196:199], v183 offset:55296
	ds_read_b128 v[200:203], v183 offset:56320
	s_nop 0
	global_load_lds_dwordx4 v178, s[50:51]
	s_add_i32 m0, s52, 0x2000
	s_nop 0
	global_load_lds_dwordx4 v182, s[50:51]
	s_add_u32 s50, s54, 0x80
	s_addc_u32 s51, s55, 0
	s_add_i32 s52, s91, s3
	s_mov_b32 m0, s52
	s_nop 0
	global_load_lds_dwordx4 v178, s[50:51]
	s_add_i32 m0, s52, 0x2000
	s_nop 0
	global_load_lds_dwordx4 v182, s[50:51]
	s_mov_b32 m0, s61
	s_nop 0
	global_load_lds_dwordx4 v176, s[48:49]
	s_mov_b32 m0, s63
	s_nop 0
	global_load_lds_dwordx4 v180, s[48:49]
	s_waitcnt vmcnt(8)
	s_waitcnt lgkmcnt(0)
	s_barrier
	s_setprio 1
	s_waitcnt lgkmcnt(0)
	v_mfma_f32_16x16x32_bf16 v[60:63], v[128:131], v[160:163], v[60:63]
	v_mfma_f32_16x16x32_bf16 v[56:59], v[136:139], v[160:163], v[56:59]
	v_mfma_f32_16x16x32_bf16 v[48:51], v[136:139], v[168:171], v[48:51]
	v_mfma_f32_16x16x32_bf16 v[52:55], v[128:131], v[168:171], v[52:55]
	v_mfma_f32_16x16x32_bf16 v[44:47], v[128:131], v[188:191], v[44:47]
	v_mfma_f32_16x16x32_bf16 v[40:43], v[136:139], v[188:191], v[40:43]
	v_mfma_f32_16x16x32_bf16 v[32:35], v[136:139], v[196:199], v[32:35]
	v_mfma_f32_16x16x32_bf16 v[36:39], v[128:131], v[196:199], v[36:39]
	v_mfma_f32_16x16x32_bf16 v[4:7], v[144:147], v[196:199], v[4:7]
	v_mfma_f32_16x16x32_bf16 v[0:3], v[152:155], v[196:199], v[0:3]
	v_mfma_f32_16x16x32_bf16 v[8:11], v[152:155], v[188:191], v[8:11]
	v_mfma_f32_16x16x32_bf16 v[12:15], v[144:147], v[188:191], v[12:15]
	v_mfma_f32_16x16x32_bf16 v[20:23], v[144:147], v[168:171], v[20:23]
	v_mfma_f32_16x16x32_bf16 v[16:19], v[152:155], v[168:171], v[16:19]
	v_mfma_f32_16x16x32_bf16 v[24:27], v[152:155], v[160:163], v[24:27]
	v_mfma_f32_16x16x32_bf16 v[28:31], v[144:147], v[160:163], v[28:31]
	v_mfma_f32_16x16x32_bf16 v[60:63], v[132:135], v[164:167], v[60:63]
	v_mfma_f32_16x16x32_bf16 v[56:59], v[140:143], v[164:167], v[56:59]
	v_mfma_f32_16x16x32_bf16 v[48:51], v[140:143], v[172:175], v[48:51]
	v_mfma_f32_16x16x32_bf16 v[52:55], v[132:135], v[172:175], v[52:55]
	v_mfma_f32_16x16x32_bf16 v[44:47], v[132:135], v[192:195], v[44:47]
	v_mfma_f32_16x16x32_bf16 v[40:43], v[140:143], v[192:195], v[40:43]
	v_mfma_f32_16x16x32_bf16 v[32:35], v[140:143], v[200:203], v[32:35]
	v_mfma_f32_16x16x32_bf16 v[36:39], v[132:135], v[200:203], v[36:39]
	v_mfma_f32_16x16x32_bf16 v[4:7], v[148:151], v[200:203], v[4:7]
	v_mfma_f32_16x16x32_bf16 v[0:3], v[156:159], v[200:203], v[0:3]
	v_mfma_f32_16x16x32_bf16 v[8:11], v[156:159], v[192:195], v[8:11]
	v_mfma_f32_16x16x32_bf16 v[12:15], v[148:151], v[192:195], v[12:15]
	v_mfma_f32_16x16x32_bf16 v[20:23], v[148:151], v[172:175], v[20:23]
	v_mfma_f32_16x16x32_bf16 v[16:19], v[156:159], v[172:175], v[16:19]
	v_mfma_f32_16x16x32_bf16 v[24:27], v[156:159], v[164:167], v[24:27]
	v_mfma_f32_16x16x32_bf16 v[28:31], v[148:151], v[164:167], v[28:31]
	s_setprio 0
	s_barrier
	s_add_u32 s85, s85, 0x100
	s_addc_u32 s86, s86, 0
	s_add_u32 s87, s87, 0x10000
	s_addc_u32 s88, s88, 0
	s_cmp_ge_u32 s89, s83
	s_mov_b32 s48, s89
	s_cbranch_scc0 .LBB0_1287
	s_and_b64 vcc, exec, s[42:43]
	s_cbranch_vccnz .LBB0_1292
	s_cmp_lt_i32 s36, 0
	s_mov_b64 s[48:49], -1
	s_cbranch_scc1 .LBB0_1293
